# half-wave row reductions in the attention and retention epilogues: xor-1/2/4/8 butterfly steps done with DPP adds instead of ds_bpermute round trips
# baseline (speedup 1.0000x reference)
; #define LAS __attribute__((address_space(3)))
; DI bf16_t f2bf1(float f) { return (bf16_t)(pk2(f, 0.f) & 0xffffu); }
; DI int crow(int r, int hi) { return (r & 3) + 8 * (r >> 2) + 4 * hi; }
; template <bool SHIFT> DI void phase_attn2(const Params& p, const Grp& G, int layer, LAS unsigned char* lds, int tid, int wave, int lane, int vcu, bool dry) {
;     ...
;         for (int cb = 0; cb < 4; ++cb) sw[cb] = p.subln[layer * 128 + 32 * cb + l31v] * (1.0f - lam_init);
;         LAS float* ex = (LAS float*)lds + qg * 4096;
; #pragma unroll
;         for (int rbq = 0; rbq < 2; ++rbq) {
; #pragma unroll
;             for (int r = 0; r < 16; ++r) { const float rl = __builtin_amdgcn_rcpf(lscr[32 * rbq + crow(r, hiv)]);
; #pragma unroll
;                 for (int cb = 0; cb < 4; ++cb) o[rbq][cb][r] *= rl; }
;             if (c == 1) {
; #pragma unroll
;                 for (int cb = 0; cb < 4; ++cb)
; #pragma unroll
;                     for (int r = 0; r < 16; ++r) ex[crow(r, hiv) * 128 + 32 * cb + l31v] = o[rbq][cb][r];
;             }
;             __syncthreads();
;             if (c == 0) {
;                 LAS unsigned char* stg = lds + AT2_QS + wave * 8192;
; #pragma unroll
;                 for (int r = 0; r < 16; ++r) {
;                     float a[4]; float ss = 0.f;
; #pragma unroll
;                     for (int cb = 0; cb < 4; ++cb) { a[cb] = o[rbq][cb][r] - lamv * ex[crow(r, hiv) * 128 + 32 * cb + l31v]; ss += a[cb] * a[cb]; }
;                     ss = half_sum32(ss); const float ri = rsqrtf(ss * (1.0f / 128.0f) + EPSN);
;                     LAS bf16_t* sp = (LAS bf16_t*)(stg + crow(r, hiv) * 256) + l31v;
; #pragma unroll
;                     for (int cb = 0; cb < 4; ++cb) sp[32 * cb] = f2bf1(a[cb] * ri * sw[cb]);
.LBB0_392:
	v_sub_f32_e32 v64, 1.0, v158
	s_waitcnt vmcnt(3)
	v_mul_f32_e32 v105, v64, v160
	s_waitcnt vmcnt(2)
	v_mul_f32_e32 v104, v64, v161
	s_waitcnt vmcnt(1)
	v_mul_f32_e32 v95, v64, v162
	s_waitcnt vmcnt(0)
	v_mul_f32_e32 v93, v64, v163
	v_lshlrev_b32_e32 v64, 1, v157
	v_lshlrev_b32_e32 v65, 10, v159
	v_readlane_b32 s8, v253, 9
	s_lshl_b64 s[0:1], s[40:41], 11
	s_add_u32 s0, s28, s0
	v_add3_u32 v94, s8, v64, v65
	v_lshlrev_b32_e32 v64, 4, v128
	v_and_b32_e32 v192, 0xf0, v64
	s_addc_u32 s1, s29, s1
	v_add_u32_e32 v92, s8, v192
	s_lshl_b32 s8, s59, 1
	s_add_u32 s0, s0, s8
	s_addc_u32 s1, s1, 0
	v_lshl_add_u64 v[64:65], s[0:1], 0, v[192:193]
	v_readlane_b32 s0, v253, 13
	v_readlane_b32 s1, v253, 14
	s_andn2_b64 vcc, exec, s[0:1]
	s_waitcnt lgkmcnt(0)
	v_cndmask_b32_e64 v78, 0, 1, s[0:1]
	v_cmp_ne_u32_e64 s[40:41], 1, v78
	s_barrier
	s_cbranch_vccnz .LBB0_394
	ds_read2_b32 v[78:79], v129 offset1:32
	ds_read2_b32 v[120:121], v129 offset0:64 offset1:96
	ds_read2_b32 v[122:123], v129 offset0:128 offset1:160
	ds_read2_b32 v[124:125], v129 offset0:192 offset1:224
	s_mov_b32 s0, 0x358637bd
	s_waitcnt lgkmcnt(3)
	v_pk_fma_f32 v[126:127], s[30:31], v[78:79], v[148:149] op_sel_hi:[0,1,1] neg_lo:[1,0,0] neg_hi:[1,0,0]
	s_waitcnt lgkmcnt(2)
	v_pk_fma_f32 v[120:121], s[30:31], v[120:121], v[150:151] op_sel_hi:[0,1,1] neg_lo:[1,0,0] neg_hi:[1,0,0]
	s_waitcnt lgkmcnt(1)
	v_pk_fma_f32 v[122:123], s[30:31], v[122:123], v[154:155] op_sel_hi:[0,1,1] neg_lo:[1,0,0] neg_hi:[1,0,0]
	v_pk_mul_f32 v[78:79], v[126:127], v[126:127]
	v_pk_mul_f32 v[150:151], v[122:123], v[122:123]
	s_waitcnt lgkmcnt(0)
	v_pk_fma_f32 v[124:125], s[30:31], v[124:125], v[152:153] op_sel_hi:[0,1,1] neg_lo:[1,0,0] neg_hi:[1,0,0]
	v_pk_mul_f32 v[148:149], v[120:121], v[120:121]
	v_pk_mul_f32 v[152:153], v[124:125], v[124:125]
	v_mov_b32_e32 v154, v150
	v_mov_b32_e32 v155, v78
	v_mov_b32_e32 v78, v151
	v_pk_add_f32 v[78:79], v[154:155], v[78:79]
	v_mov_b32_e32 v150, v152
	v_mov_b32_e32 v151, v148
	v_pk_add_f32 v[78:79], v[78:79], v[150:151]
	v_mov_b32_e32 v148, v153
	v_pk_add_f32 v[78:79], v[78:79], v[148:149]
	s_waitcnt lgkmcnt(0)
	s_nop 1
	v_add_f32_dpp v78, v78, v78 quad_perm:[1,0,3,2] row_mask:0xf bank_mask:0xf
	v_add_f32_dpp v79, v79, v79 quad_perm:[1,0,3,2] row_mask:0xf bank_mask:0xf
	s_waitcnt lgkmcnt(0)
	s_nop 1
	v_add_f32_dpp v78, v78, v78 quad_perm:[2,3,0,1] row_mask:0xf bank_mask:0xf
	v_add_f32_dpp v79, v79, v79 quad_perm:[2,3,0,1] row_mask:0xf bank_mask:0xf
	s_waitcnt lgkmcnt(0)
	s_nop 1
	v_add_f32_dpp v78, v78, v78 row_half_mirror row_mask:0xf bank_mask:0xf
	v_add_f32_dpp v79, v79, v79 row_half_mirror row_mask:0xf bank_mask:0xf
	s_waitcnt lgkmcnt(0)
	s_nop 1
	v_add_f32_dpp v148, v78, v78 row_ror:8 row_mask:0xf bank_mask:0xf
	v_add_f32_dpp v149, v79, v79 row_ror:8 row_mask:0xf bank_mask:0xf
	ds_bpermute_b32 v151, v215, v149
	ds_bpermute_b32 v150, v215, v148
	v_mov_b64_e32 v[78:79], s[0:1]
	s_brev_b32 s0, 60
	s_waitcnt lgkmcnt(0)
	v_pk_add_f32 v[148:149], v[148:149], v[150:151]
	s_nop 0
	v_pk_fma_f32 v[148:149], v[148:149], s[0:1], v[78:79] op_sel_hi:[1,0,0]
	s_nop 0
	v_mul_f32_e32 v119, 0x4b800000, v149
	v_cmp_gt_f32_e32 vcc, s90, v149
	s_nop 1
	v_cndmask_b32_e32 v119, v149, v119, vcc
	v_rsq_f32_e32 v119, v119
	s_nop 0
	v_mul_f32_e32 v149, 0x45800000, v119
	v_cndmask_b32_e32 v119, v119, v149, vcc
	v_mul_f32_e32 v126, v126, v119
	v_mul_f32_e32 v127, v127, v119
	v_mul_f32_e32 v126, v105, v126
	v_mul_f32_e32 v127, v104, v127
	v_cvt_pk_bf16_f32 v126, v126, s0
	v_cvt_pk_bf16_f32 v127, v127, s0
	ds_write_b16 v94, v126
	ds_write_b16 v94, v127 offset:64
	ds_read2_b32 v[126:127], v118 offset1:32
	v_mul_f32_e32 v120, v120, v119
	v_mul_f32_e32 v120, v95, v120
	v_cvt_pk_bf16_f32 v120, v120, s0
	ds_write_b16 v94, v120 offset:128
	s_waitcnt lgkmcnt(1)
	v_pk_fma_f32 v[126:127], s[30:31], v[126:127], v[142:143] op_sel_hi:[0,1,1] neg_lo:[1,0,0] neg_hi:[1,0,0]
	ds_read2_b32 v[142:143], v118 offset0:128 offset1:160
	v_mul_f32_e32 v119, v121, v119
	ds_read2_b32 v[120:121], v118 offset0:64 offset1:96
	ds_read2_b32 v[152:153], v118 offset0:192 offset1:224
	v_pk_mul_f32 v[150:151], v[126:127], v[126:127]
	s_waitcnt lgkmcnt(2)
	v_pk_fma_f32 v[142:143], s[30:31], v[142:143], v[146:147] op_sel_hi:[0,1,1] neg_lo:[1,0,0] neg_hi:[1,0,0]
	v_pk_mul_f32 v[146:147], v[142:143], v[142:143]
	s_waitcnt lgkmcnt(1)
	v_pk_fma_f32 v[120:121], s[30:31], v[120:121], v[140:141] op_sel_hi:[0,1,1] neg_lo:[1,0,0] neg_hi:[1,0,0]
	s_waitcnt lgkmcnt(0)
	v_pk_fma_f32 v[144:145], s[30:31], v[152:153], v[144:145] op_sel_hi:[0,1,1] neg_lo:[1,0,0] neg_hi:[1,0,0]
	v_pk_mul_f32 v[140:141], v[120:121], v[120:121]
	v_pk_mul_f32 v[152:153], v[144:145], v[144:145]
	v_mov_b32_e32 v154, v146
	v_mov_b32_e32 v155, v150
	v_mov_b32_e32 v150, v147
	v_pk_add_f32 v[146:147], v[154:155], v[150:151]
	v_mov_b32_e32 v150, v152
	v_mov_b32_e32 v151, v140
	v_pk_add_f32 v[146:147], v[146:147], v[150:151]
	v_mov_b32_e32 v140, v153
	v_pk_add_f32 v[140:141], v[146:147], v[140:141]
	v_mul_f32_e32 v149, 0x4b800000, v148
	v_cmp_gt_f32_e32 vcc, s90, v148
	v_mul_f32_e32 v119, v93, v119
	v_cvt_pk_bf16_f32 v119, v119, s0
	s_waitcnt lgkmcnt(0)
	s_nop 1
	v_add_f32_dpp v140, v140, v140 quad_perm:[1,0,3,2] row_mask:0xf bank_mask:0xf
	v_add_f32_dpp v141, v141, v141 quad_perm:[1,0,3,2] row_mask:0xf bank_mask:0xf
	v_cndmask_b32_e32 v148, v148, v149, vcc
	v_rsq_f32_e32 v148, v148
	ds_write_b16 v94, v119 offset:192
	s_waitcnt lgkmcnt(1)
	s_nop 1
	v_add_f32_dpp v140, v140, v140 quad_perm:[2,3,0,1] row_mask:0xf bank_mask:0xf
	v_add_f32_dpp v141, v141, v141 quad_perm:[2,3,0,1] row_mask:0xf bank_mask:0xf
	v_mul_f32_e32 v119, 0x45800000, v148
	v_cndmask_b32_e32 v119, v148, v119, vcc
	v_mul_f32_e32 v122, v122, v119
	v_mul_f32_e32 v122, v105, v122
	v_cvt_pk_bf16_f32 v122, v122, s0
	ds_write_b16 v94, v122 offset:256
	v_mul_f32_e32 v148, v123, v119
	s_waitcnt lgkmcnt(1)
; #define LAS __attribute__((address_space(3)))
; DI bf16_t f2bf1(float f) { return (bf16_t)(pk2(f, 0.f) & 0xffffu); }
; DI int crow(int r, int hi) { return (r & 3) + 8 * (r >> 2) + 4 * hi; }
; template <bool SHIFT> DI void phase_attn2(const Params& p, const Grp& G, int layer, LAS unsigned char* lds, int tid, int wave, int lane, int vcu, bool dry) {
;     ...
;                 for (int r = 0; r < 16; ++r) {
;                     float a[4]; float ss = 0.f;
; #pragma unroll
;                     for (int cb = 0; cb < 4; ++cb) { a[cb] = o[rbq][cb][r] - lamv * ex[crow(r, hiv) * 128 + 32 * cb + l31v]; ss += a[cb] * a[cb]; }
;                     ss = half_sum32(ss); const float ri = rsqrtf(ss * (1.0f / 128.0f) + EPSN);
;                     LAS bf16_t* sp = (LAS bf16_t*)(stg + crow(r, hiv) * 256) + l31v;
; #pragma unroll
;                     for (int cb = 0; cb < 4; ++cb) sp[32 * cb] = f2bf1(a[cb] * ri * sw[cb]);
	s_nop 1
	v_add_f32_dpp v122, v140, v140 row_half_mirror row_mask:0xf bank_mask:0xf
	v_add_f32_dpp v123, v141, v141 row_half_mirror row_mask:0xf bank_mask:0xf
	v_mul_f32_e32 v124, v124, v119
	v_mul_f32_e32 v124, v95, v124
	v_cvt_pk_bf16_f32 v124, v124, s0
	ds_write_b16 v94, v124 offset:384
	s_waitcnt lgkmcnt(1)
	s_nop 1
	v_add_f32_dpp v122, v122, v122 row_ror:8 row_mask:0xf bank_mask:0xf
	v_add_f32_dpp v123, v123, v123 row_ror:8 row_mask:0xf bank_mask:0xf
	ds_bpermute_b32 v141, v215, v123
	ds_bpermute_b32 v140, v215, v122
	v_mul_f32_e32 v119, v125, v119
	v_mul_f32_e32 v119, v93, v119
	v_cvt_pk_bf16_f32 v119, v119, s0
	ds_write_b16 v94, v119 offset:448
	s_waitcnt lgkmcnt(1)
	v_pk_add_f32 v[122:123], v[122:123], v[140:141]
	ds_read2_b32 v[140:141], v111 offset0:192 offset1:224
	v_pk_fma_f32 v[122:123], v[122:123], s[0:1], v[78:79] op_sel_hi:[1,0,0]
	v_mul_f32_e32 v146, v104, v148
	v_mul_f32_e32 v124, 0x4b800000, v123
	v_cmp_gt_f32_e32 vcc, s90, v123
	v_cvt_pk_bf16_f32 v146, v146, s0
	s_waitcnt lgkmcnt(0)
	v_pk_fma_f32 v[136:137], s[30:31], v[140:141], v[136:137] op_sel_hi:[0,1,1] neg_lo:[1,0,0] neg_hi:[1,0,0]
	v_cndmask_b32_e32 v123, v123, v124, vcc
	v_rsq_f32_e32 v123, v123
	ds_read2_b32 v[124:125], v111 offset1:32
	ds_write_b16 v94, v146 offset:320
	v_pk_mul_f32 v[140:141], v[136:137], v[136:137]
	v_mul_f32_e32 v119, 0x45800000, v123
	v_cndmask_b32_e32 v119, v123, v119, vcc
	v_mul_f32_e32 v123, v126, v119
	v_mul_f32_e32 v123, v105, v123
	v_mul_f32_e32 v120, v120, v119
	v_cvt_pk_bf16_f32 v123, v123, s0
	v_mul_f32_e32 v120, v95, v120
	ds_write_b16 v94, v123 offset:512
	v_mul_f32_e32 v123, v127, v119
	v_cvt_pk_bf16_f32 v120, v120, s0
	ds_read2_b32 v[126:127], v111 offset0:128 offset1:160
	ds_write_b16 v94, v120 offset:640
	v_mul_f32_e32 v119, v121, v119
	ds_read2_b32 v[120:121], v111 offset0:64 offset1:96
	s_waitcnt lgkmcnt(5)
	v_pk_fma_f32 v[124:125], s[30:31], v[124:125], v[134:135] op_sel_hi:[0,1,1] neg_lo:[1,0,0] neg_hi:[1,0,0]
	s_waitcnt lgkmcnt(2)
	v_pk_fma_f32 v[126:127], s[30:31], v[126:127], v[138:139] op_sel_hi:[0,1,1] neg_lo:[1,0,0] neg_hi:[1,0,0]
	v_pk_mul_f32 v[134:135], v[124:125], v[124:125]
	v_pk_mul_f32 v[138:139], v[126:127], v[126:127]
	s_waitcnt lgkmcnt(0)
	v_pk_fma_f32 v[120:121], s[30:31], v[120:121], v[132:133] op_sel_hi:[0,1,1] neg_lo:[1,0,0] neg_hi:[1,0,0]
	v_pk_mul_f32 v[132:133], v[120:121], v[120:121]
	v_mov_b32_e32 v146, v138
	v_mov_b32_e32 v147, v134
	v_mov_b32_e32 v134, v139
	v_pk_add_f32 v[134:135], v[146:147], v[134:135]
	v_mov_b32_e32 v138, v140
	v_mov_b32_e32 v139, v132
	v_pk_add_f32 v[134:135], v[134:135], v[138:139]
	v_mov_b32_e32 v132, v141
	v_pk_add_f32 v[132:133], v[134:135], v[132:133]
	v_mul_f32_e32 v123, v104, v123
	v_cvt_pk_bf16_f32 v123, v123, s0
	ds_write_b16 v94, v123 offset:576
	v_mul_f32_e32 v123, 0x4b800000, v122
	v_cmp_gt_f32_e32 vcc, s90, v122
	v_mul_f32_e32 v119, v93, v119
	v_cvt_pk_bf16_f32 v119, v119, s0
	v_cndmask_b32_e32 v122, v122, v123, vcc
	v_rsq_f32_e32 v138, v122
	s_waitcnt lgkmcnt(1)
	s_nop 1
	v_add_f32_dpp v122, v132, v132 quad_perm:[1,0,3,2] row_mask:0xf bank_mask:0xf
	v_add_f32_dpp v123, v133, v133 quad_perm:[1,0,3,2] row_mask:0xf bank_mask:0xf
	ds_write_b16 v94, v119 offset:704
	v_mul_f32_e32 v119, 0x45800000, v138
	v_cndmask_b32_e32 v119, v138, v119, vcc
	v_mul_f32_e32 v134, v142, v119
	s_waitcnt lgkmcnt(1)
	s_nop 1
	v_add_f32_dpp v122, v122, v122 quad_perm:[2,3,0,1] row_mask:0xf bank_mask:0xf
	v_add_f32_dpp v123, v123, v123 quad_perm:[2,3,0,1] row_mask:0xf bank_mask:0xf
	v_mul_f32_e32 v134, v105, v134
	v_cvt_pk_bf16_f32 v134, v134, s0
	ds_write_b16 v94, v134 offset:768
	v_mul_f32_e32 v134, v143, v119
	s_waitcnt lgkmcnt(1)
	s_nop 1
	v_add_f32_dpp v122, v122, v122 row_half_mirror row_mask:0xf bank_mask:0xf
	v_add_f32_dpp v123, v123, v123 row_half_mirror row_mask:0xf bank_mask:0xf
	v_mul_f32_e32 v134, v104, v134
	v_cvt_pk_bf16_f32 v134, v134, s0
	ds_write_b16 v94, v134 offset:832
	v_mul_f32_e32 v134, v144, v119
	s_waitcnt lgkmcnt(1)
	s_nop 1
	v_add_f32_dpp v122, v122, v122 row_ror:8 row_mask:0xf bank_mask:0xf
	v_add_f32_dpp v123, v123, v123 row_ror:8 row_mask:0xf bank_mask:0xf
	ds_bpermute_b32 v133, v215, v123
	ds_bpermute_b32 v132, v215, v122
	v_mul_f32_e32 v119, v145, v119
	v_mul_f32_e32 v119, v93, v119
	v_cvt_pk_bf16_f32 v119, v119, s0
	ds_write_b16 v94, v119 offset:960
	s_waitcnt lgkmcnt(1)
	v_pk_add_f32 v[122:123], v[122:123], v[132:133]
	v_mul_f32_e32 v134, v95, v134
	v_pk_fma_f32 v[122:123], v[122:123], s[0:1], v[78:79] op_sel_hi:[1,0,0]
	v_cvt_pk_bf16_f32 v134, v134, s0
	v_mul_f32_e32 v132, 0x4b800000, v123
	v_cmp_gt_f32_e32 vcc, s90, v123
	ds_write_b16 v94, v134 offset:896
	ds_read2_b32 v[134:135], v110 offset0:192 offset1:224
	v_cndmask_b32_e32 v123, v123, v132, vcc
	v_rsq_f32_e32 v123, v123
	s_waitcnt lgkmcnt(0)
	v_pk_fma_f32 v[114:115], s[30:31], v[134:135], v[114:115] op_sel_hi:[0,1,1] neg_lo:[1,0,0] neg_hi:[1,0,0]
	v_mul_f32_e32 v119, 0x45800000, v123
	v_cndmask_b32_e32 v119, v123, v119, vcc
	v_mul_f32_e32 v123, v124, v119
	v_mul_f32_e32 v123, v105, v123
	v_cvt_pk_bf16_f32 v123, v123, s0
	ds_write_b16 v94, v123 offset:2048
	v_mul_f32_e32 v123, v125, v119
	ds_read2_b32 v[124:125], v110 offset1:32
	v_mul_f32_e32 v120, v120, v119
	v_mul_f32_e32 v120, v95, v120
	v_cvt_pk_bf16_f32 v120, v120, s0
	ds_write_b16 v94, v120 offset:2176
	s_waitcnt lgkmcnt(1)
	v_pk_fma_f32 v[124:125], s[30:31], v[124:125], v[130:131] op_sel_hi:[0,1,1] neg_lo:[1,0,0] neg_hi:[1,0,0]
	ds_read2_b32 v[130:131], v110 offset0:128 offset1:160
	v_mul_f32_e32 v119, v121, v119
	ds_read2_b32 v[120:121], v110 offset0:64 offset1:96
	v_pk_mul_f32 v[132:133], v[124:125], v[124:125]
	v_pk_mul_f32 v[134:135], v[114:115], v[114:115]
	s_waitcnt lgkmcnt(1)
; #define LAS __attribute__((address_space(3)))
; DI bf16_t f2bf1(float f) { return (bf16_t)(pk2(f, 0.f) & 0xffffu); }
; DI int crow(int r, int hi) { return (r & 3) + 8 * (r >> 2) + 4 * hi; }
; template <bool SHIFT> DI void phase_attn2(const Params& p, const Grp& G, int layer, LAS unsigned char* lds, int tid, int wave, int lane, int vcu, bool dry) {
;     ...
;                 for (int r = 0; r < 16; ++r) {
;                     float a[4]; float ss = 0.f;
; #pragma unroll
;                     for (int cb = 0; cb < 4; ++cb) { a[cb] = o[rbq][cb][r] - lamv * ex[crow(r, hiv) * 128 + 32 * cb + l31v]; ss += a[cb] * a[cb]; }
;                     ss = half_sum32(ss); const float ri = rsqrtf(ss * (1.0f / 128.0f) + EPSN);
;                     LAS bf16_t* sp = (LAS bf16_t*)(stg + crow(r, hiv) * 256) + l31v;
; #pragma unroll
;                     for (int cb = 0; cb < 4; ++cb) sp[32 * cb] = f2bf1(a[cb] * ri * sw[cb]);
	v_pk_fma_f32 v[116:117], s[30:31], v[130:131], v[116:117] op_sel_hi:[0,1,1] neg_lo:[1,0,0] neg_hi:[1,0,0]
	v_pk_mul_f32 v[130:131], v[116:117], v[116:117]
	s_waitcnt lgkmcnt(0)
	v_pk_fma_f32 v[112:113], s[30:31], v[120:121], v[112:113] op_sel_hi:[0,1,1] neg_lo:[1,0,0] neg_hi:[1,0,0]
	v_pk_mul_f32 v[120:121], v[112:113], v[112:113]
	v_mov_b32_e32 v138, v130
	v_mov_b32_e32 v139, v132
	v_mov_b32_e32 v132, v131
	v_pk_add_f32 v[130:131], v[138:139], v[132:133]
	v_mov_b32_e32 v132, v134
	v_mov_b32_e32 v133, v120
	v_pk_add_f32 v[130:131], v[130:131], v[132:133]
	v_mov_b32_e32 v120, v135
	v_pk_add_f32 v[120:121], v[130:131], v[120:121]
	v_mul_f32_e32 v123, v104, v123
	v_cvt_pk_bf16_f32 v123, v123, s0
	ds_write_b16 v94, v123 offset:2112
	v_mul_f32_e32 v123, 0x4b800000, v122
	v_cmp_gt_f32_e32 vcc, s90, v122
	s_waitcnt lgkmcnt(1)
	s_nop 1
	v_add_f32_dpp v120, v120, v120 quad_perm:[1,0,3,2] row_mask:0xf bank_mask:0xf
	v_add_f32_dpp v121, v121, v121 quad_perm:[1,0,3,2] row_mask:0xf bank_mask:0xf
	v_mul_f32_e32 v119, v93, v119
	v_cndmask_b32_e32 v122, v122, v123, vcc
	v_rsq_f32_e32 v132, v122
	v_cvt_pk_bf16_f32 v119, v119, s0
	ds_write_b16 v94, v119 offset:2240
	v_mul_f32_e32 v119, 0x45800000, v132
	v_cndmask_b32_e32 v119, v132, v119, vcc
	s_waitcnt lgkmcnt(1)
	s_nop 1
	v_add_f32_dpp v120, v120, v120 quad_perm:[2,3,0,1] row_mask:0xf bank_mask:0xf
	v_add_f32_dpp v121, v121, v121 quad_perm:[2,3,0,1] row_mask:0xf bank_mask:0xf
	v_mul_f32_e32 v126, v126, v119
	v_mul_f32_e32 v126, v105, v126
	v_cvt_pk_bf16_f32 v126, v126, s0
	ds_write_b16 v94, v126 offset:2304
	s_waitcnt lgkmcnt(1)
	s_nop 1
	v_add_f32_dpp v120, v120, v120 row_half_mirror row_mask:0xf bank_mask:0xf
	v_add_f32_dpp v121, v121, v121 row_half_mirror row_mask:0xf bank_mask:0xf
	v_mul_f32_e32 v126, v127, v119
	v_mul_f32_e32 v126, v104, v126
	v_cvt_pk_bf16_f32 v126, v126, s0
	ds_write_b16 v94, v126 offset:2368
	s_waitcnt lgkmcnt(1)
	s_nop 1
	v_add_f32_dpp v120, v120, v120 row_ror:8 row_mask:0xf bank_mask:0xf
	v_add_f32_dpp v121, v121, v121 row_ror:8 row_mask:0xf bank_mask:0xf
	ds_bpermute_b32 v123, v215, v121
	ds_bpermute_b32 v122, v215, v120
	v_mul_f32_e32 v126, v136, v119
	v_mul_f32_e32 v119, v137, v119
	v_mul_f32_e32 v119, v93, v119
	v_cvt_pk_bf16_f32 v119, v119, s0
	s_waitcnt lgkmcnt(0)
	v_pk_add_f32 v[120:121], v[120:121], v[122:123]
	ds_write_b16 v94, v119 offset:2496
	v_pk_fma_f32 v[120:121], v[120:121], s[0:1], v[78:79] op_sel_hi:[1,0,0]
	v_mul_f32_e32 v126, v95, v126
	v_mul_f32_e32 v122, 0x4b800000, v121
	v_cmp_gt_f32_e32 vcc, s90, v121
	v_cvt_pk_bf16_f32 v126, v126, s0
	ds_write_b16 v94, v126 offset:2432
	v_cndmask_b32_e32 v121, v121, v122, vcc
	v_rsq_f32_e32 v121, v121
	ds_read2_b32 v[122:123], v109 offset1:32
	ds_read2_b32 v[126:127], v109 offset0:192 offset1:224
	v_mul_f32_e32 v119, 0x45800000, v121
	v_cndmask_b32_e32 v119, v121, v119, vcc
	v_mul_f32_e32 v112, v112, v119
	v_mul_f32_e32 v112, v95, v112
	v_mul_f32_e32 v121, v124, v119
	v_cvt_pk_bf16_f32 v112, v112, s0
	v_mul_f32_e32 v121, v105, v121
	ds_write_b16 v94, v112 offset:2688
	v_mul_f32_e32 v112, v113, v119
	v_cvt_pk_bf16_f32 v121, v121, s0
	v_mul_f32_e32 v112, v93, v112
	s_waitcnt lgkmcnt(2)
	v_pk_fma_f32 v[102:103], s[30:31], v[122:123], v[102:103] op_sel_hi:[0,1,1] neg_lo:[1,0,0] neg_hi:[1,0,0]
	ds_read2_b32 v[122:123], v109 offset0:128 offset1:160
	ds_write_b16 v94, v121 offset:2560
	v_mul_f32_e32 v121, v125, v119
	v_cvt_pk_bf16_f32 v119, v112, s0
	ds_read2_b32 v[112:113], v109 offset0:64 offset1:96
	s_waitcnt lgkmcnt(2)
	v_pk_fma_f32 v[100:101], s[30:31], v[122:123], v[100:101] op_sel_hi:[0,1,1] neg_lo:[1,0,0] neg_hi:[1,0,0]
	v_pk_mul_f32 v[124:125], v[102:103], v[102:103]
	v_pk_mul_f32 v[122:123], v[100:101], v[100:101]
	v_pk_fma_f32 v[96:97], s[30:31], v[126:127], v[96:97] op_sel_hi:[0,1,1] neg_lo:[1,0,0] neg_hi:[1,0,0]
	s_waitcnt lgkmcnt(0)
	v_pk_fma_f32 v[98:99], s[30:31], v[112:113], v[98:99] op_sel_hi:[0,1,1] neg_lo:[1,0,0] neg_hi:[1,0,0]
	v_pk_mul_f32 v[112:113], v[98:99], v[98:99]
	v_pk_mul_f32 v[126:127], v[96:97], v[96:97]
	v_mov_b32_e32 v130, v122
	v_mov_b32_e32 v131, v124
	v_mov_b32_e32 v124, v123
	v_pk_add_f32 v[122:123], v[130:131], v[124:125]
	v_mov_b32_e32 v124, v126
	v_mov_b32_e32 v125, v112
	v_pk_add_f32 v[122:123], v[122:123], v[124:125]
	v_mov_b32_e32 v112, v127
	v_pk_add_f32 v[112:113], v[122:123], v[112:113]
	v_mul_f32_e32 v121, v104, v121
	v_cvt_pk_bf16_f32 v121, v121, s0
	ds_write_b16 v94, v121 offset:2624
	v_mul_f32_e32 v121, 0x4b800000, v120
	v_cmp_gt_f32_e32 vcc, s90, v120
	s_waitcnt lgkmcnt(1)
	s_nop 1
	v_add_f32_dpp v112, v112, v112 quad_perm:[1,0,3,2] row_mask:0xf bank_mask:0xf
	v_add_f32_dpp v113, v113, v113 quad_perm:[1,0,3,2] row_mask:0xf bank_mask:0xf
	ds_write_b16 v94, v119 offset:2752
	v_cndmask_b32_e32 v120, v120, v121, vcc
	v_rsq_f32_e32 v124, v120
	v_mul_f32_e32 v119, 0x45800000, v124
	v_cndmask_b32_e32 v119, v124, v119, vcc
	v_mul_f32_e32 v116, v116, v119
	s_waitcnt lgkmcnt(0)
	s_nop 1
	v_add_f32_dpp v112, v112, v112 quad_perm:[2,3,0,1] row_mask:0xf bank_mask:0xf
	v_add_f32_dpp v113, v113, v113 quad_perm:[2,3,0,1] row_mask:0xf bank_mask:0xf
	v_mul_f32_e32 v116, v105, v116
	v_cvt_pk_bf16_f32 v116, v116, s0
	ds_write_b16 v94, v116 offset:2816
	v_mul_f32_e32 v122, v117, v119
	s_waitcnt lgkmcnt(1)
	s_nop 1
	v_add_f32_dpp v112, v112, v112 row_half_mirror row_mask:0xf bank_mask:0xf
	v_add_f32_dpp v113, v113, v113 row_half_mirror row_mask:0xf bank_mask:0xf
	v_mul_f32_e32 v114, v114, v119
	v_mul_f32_e32 v114, v95, v114
	v_cvt_pk_bf16_f32 v114, v114, s0
	ds_write_b16 v94, v114 offset:2944
	s_waitcnt lgkmcnt(1)
; #define LAS __attribute__((address_space(3)))
; DI bf16_t f2bf1(float f) { return (bf16_t)(pk2(f, 0.f) & 0xffffu); }
; DI int crow(int r, int hi) { return (r & 3) + 8 * (r >> 2) + 4 * hi; }
; template <bool SHIFT> DI void phase_attn2(const Params& p, const Grp& G, int layer, LAS unsigned char* lds, int tid, int wave, int lane, int vcu, bool dry) {
;     ...
;                 for (int r = 0; r < 16; ++r) {
;                     float a[4]; float ss = 0.f;
; #pragma unroll
;                     for (int cb = 0; cb < 4; ++cb) { a[cb] = o[rbq][cb][r] - lamv * ex[crow(r, hiv) * 128 + 32 * cb + l31v]; ss += a[cb] * a[cb]; }
;                     ss = half_sum32(ss); const float ri = rsqrtf(ss * (1.0f / 128.0f) + EPSN);
;                     LAS bf16_t* sp = (LAS bf16_t*)(stg + crow(r, hiv) * 256) + l31v;
; #pragma unroll
;                     for (int cb = 0; cb < 4; ++cb) sp[32 * cb] = f2bf1(a[cb] * ri * sw[cb]);
	s_nop 1
	v_add_f32_dpp v112, v112, v112 row_ror:8 row_mask:0xf bank_mask:0xf
	v_add_f32_dpp v113, v113, v113 row_ror:8 row_mask:0xf bank_mask:0xf
	ds_bpermute_b32 v117, v215, v113
	ds_bpermute_b32 v116, v215, v112
	v_mul_f32_e32 v114, v115, v119
	v_mul_f32_e32 v114, v93, v114
	v_cvt_pk_bf16_f32 v114, v114, s0
	ds_write_b16 v94, v114 offset:3008
	s_waitcnt lgkmcnt(1)
	v_pk_add_f32 v[112:113], v[112:113], v[116:117]
	ds_read2_b32 v[116:117], v108 offset0:192 offset1:224
	v_pk_fma_f32 v[112:113], v[112:113], s[0:1], v[78:79] op_sel_hi:[1,0,0]
	v_mul_f32_e32 v120, v104, v122
	v_mul_f32_e32 v115, 0x4b800000, v113
	v_cmp_gt_f32_e32 vcc, s90, v113
	v_cvt_pk_bf16_f32 v120, v120, s0
	s_waitcnt lgkmcnt(0)
	v_pk_fma_f32 v[74:75], s[30:31], v[116:117], v[74:75] op_sel_hi:[0,1,1] neg_lo:[1,0,0] neg_hi:[1,0,0]
	v_cndmask_b32_e32 v113, v113, v115, vcc
	v_rsq_f32_e32 v113, v113
	ds_write_b16 v94, v120 offset:2880
	v_pk_mul_f32 v[116:117], v[74:75], v[74:75]
	v_mul_f32_e32 v114, 0x45800000, v113
	v_cndmask_b32_e32 v113, v113, v114, vcc
	v_mul_f32_e32 v102, v102, v113
	v_mul_f32_e32 v102, v105, v102
	v_cvt_pk_bf16_f32 v102, v102, s0
	ds_write_b16 v94, v102 offset:4096
	v_mul_f32_e32 v102, v103, v113
	v_mul_f32_e32 v102, v104, v102
	v_cvt_pk_bf16_f32 v102, v102, s0
	ds_write_b16 v94, v102 offset:4160
	ds_read2_b32 v[102:103], v108 offset1:32
	v_mul_f32_e32 v98, v98, v113
	v_mul_f32_e32 v98, v95, v98
	v_cvt_pk_bf16_f32 v98, v98, s0
	ds_write_b16 v94, v98 offset:4224
	v_mul_f32_e32 v98, v99, v113
	v_mul_f32_e32 v98, v93, v98
	s_waitcnt lgkmcnt(1)
	v_pk_fma_f32 v[84:85], s[30:31], v[102:103], v[84:85] op_sel_hi:[0,1,1] neg_lo:[1,0,0] neg_hi:[1,0,0]
	ds_read2_b32 v[102:103], v108 offset0:128 offset1:160
	v_cvt_pk_bf16_f32 v113, v98, s0
	ds_read2_b32 v[98:99], v108 offset0:64 offset1:96
	v_pk_mul_f32 v[114:115], v[84:85], v[84:85]
	v_cmp_gt_f32_e32 vcc, s90, v112
	s_waitcnt lgkmcnt(1)
	v_pk_fma_f32 v[82:83], s[30:31], v[102:103], v[82:83] op_sel_hi:[0,1,1] neg_lo:[1,0,0] neg_hi:[1,0,0]
	v_pk_mul_f32 v[102:103], v[82:83], v[82:83]
	s_waitcnt lgkmcnt(0)
	v_pk_fma_f32 v[80:81], s[30:31], v[98:99], v[80:81] op_sel_hi:[0,1,1] neg_lo:[1,0,0] neg_hi:[1,0,0]
	v_pk_mul_f32 v[98:99], v[80:81], v[80:81]
	v_mov_b32_e32 v120, v102
	v_mov_b32_e32 v121, v114
	v_mov_b32_e32 v114, v103
	v_pk_add_f32 v[102:103], v[120:121], v[114:115]
	v_mov_b32_e32 v114, v116
	v_mov_b32_e32 v115, v98
	v_pk_add_f32 v[102:103], v[102:103], v[114:115]
	v_mov_b32_e32 v98, v117
	v_pk_add_f32 v[98:99], v[102:103], v[98:99]
	v_mul_f32_e32 v114, 0x4b800000, v112
	v_cndmask_b32_e32 v112, v112, v114, vcc
	v_rsq_f32_e32 v112, v112
	ds_write_b16 v94, v113 offset:4288
	s_waitcnt lgkmcnt(1)
	s_nop 1
	v_add_f32_dpp v98, v98, v98 quad_perm:[1,0,3,2] row_mask:0xf bank_mask:0xf
	v_add_f32_dpp v99, v99, v99 quad_perm:[1,0,3,2] row_mask:0xf bank_mask:0xf
	v_mul_f32_e32 v113, 0x45800000, v112
	v_cndmask_b32_e32 v112, v112, v113, vcc
	v_mul_f32_e32 v100, v100, v112
	v_mul_f32_e32 v100, v105, v100
	s_waitcnt lgkmcnt(0)
	s_nop 1
	v_add_f32_dpp v98, v98, v98 quad_perm:[2,3,0,1] row_mask:0xf bank_mask:0xf
	v_add_f32_dpp v99, v99, v99 quad_perm:[2,3,0,1] row_mask:0xf bank_mask:0xf
	v_cvt_pk_bf16_f32 v100, v100, s0
	ds_write_b16 v94, v100 offset:4352
	v_mul_f32_e32 v113, v101, v112
	v_mul_f32_e32 v96, v96, v112
	s_waitcnt lgkmcnt(1)
	s_nop 1
	v_add_f32_dpp v98, v98, v98 row_half_mirror row_mask:0xf bank_mask:0xf
	v_add_f32_dpp v99, v99, v99 row_half_mirror row_mask:0xf bank_mask:0xf
	v_mul_f32_e32 v102, v104, v113
	v_mul_f32_e32 v96, v95, v96
	v_cvt_pk_bf16_f32 v102, v102, s0
	v_cvt_pk_bf16_f32 v96, v96, s0
	s_waitcnt lgkmcnt(0)
	s_nop 1
	v_add_f32_dpp v98, v98, v98 row_ror:8 row_mask:0xf bank_mask:0xf
	v_add_f32_dpp v99, v99, v99 row_ror:8 row_mask:0xf bank_mask:0xf
	ds_bpermute_b32 v101, v215, v99
	ds_bpermute_b32 v100, v215, v98
	ds_write_b16 v94, v102 offset:4416
	ds_write_b16 v94, v96 offset:4480
	v_mul_f32_e32 v102, v97, v112
	s_waitcnt lgkmcnt(2)
	v_pk_add_f32 v[96:97], v[98:99], v[100:101]
	s_nop 0
	v_pk_fma_f32 v[96:97], v[96:97], s[0:1], v[78:79] op_sel_hi:[1,0,0]
	ds_read2_b32 v[100:101], v107 offset0:192 offset1:224
	v_mul_f32_e32 v98, 0x4b800000, v97
	v_cmp_gt_f32_e32 vcc, s90, v97
	s_waitcnt lgkmcnt(0)
	v_pk_fma_f32 v[76:77], s[30:31], v[100:101], v[76:77] op_sel_hi:[0,1,1] neg_lo:[1,0,0] neg_hi:[1,0,0]
	v_cndmask_b32_e32 v97, v97, v98, vcc
	v_rsq_f32_e32 v97, v97
	v_mul_f32_e32 v98, v93, v102
	v_cvt_pk_bf16_f32 v98, v98, s0
	ds_write_b16 v94, v98 offset:4544
	v_mul_f32_e32 v98, 0x45800000, v97
	v_cndmask_b32_e32 v97, v97, v98, vcc
	v_mul_f32_e32 v84, v84, v97
	v_mul_f32_e32 v84, v105, v84
	v_cvt_pk_bf16_f32 v84, v84, s0
	ds_write_b16 v94, v84 offset:4608
	v_mul_f32_e32 v84, v85, v97
	v_mul_f32_e32 v84, v104, v84
	v_cvt_pk_bf16_f32 v84, v84, s0
	ds_write_b16 v94, v84 offset:4672
	ds_read2_b32 v[84:85], v107 offset1:32
	v_mul_f32_e32 v80, v80, v97
	v_mul_f32_e32 v80, v95, v80
	v_cvt_pk_bf16_f32 v80, v80, s0
	ds_write_b16 v94, v80 offset:4736
	v_mul_f32_e32 v80, v81, v97
	v_mul_f32_e32 v80, v93, v80
	s_waitcnt lgkmcnt(1)
	v_pk_fma_f32 v[84:85], s[30:31], v[84:85], v[88:89] op_sel_hi:[0,1,1] neg_lo:[1,0,0] neg_hi:[1,0,0]
	ds_read2_b32 v[88:89], v107 offset0:128 offset1:160
	v_cvt_pk_bf16_f32 v97, v80, s0
	ds_read2_b32 v[80:81], v107 offset0:64 offset1:96
	v_pk_mul_f32 v[98:99], v[84:85], v[84:85]
	v_pk_mul_f32 v[100:101], v[76:77], v[76:77]
	s_waitcnt lgkmcnt(1)
	v_pk_fma_f32 v[88:89], s[30:31], v[88:89], v[90:91] op_sel_hi:[0,1,1] neg_lo:[1,0,0] neg_hi:[1,0,0]
	v_pk_mul_f32 v[90:91], v[88:89], v[88:89]
	s_waitcnt lgkmcnt(0)
; #define LAS __attribute__((address_space(3)))
; DI bf16_t f2bf1(float f) { return (bf16_t)(pk2(f, 0.f) & 0xffffu); }
; DI int crow(int r, int hi) { return (r & 3) + 8 * (r >> 2) + 4 * hi; }
; template <bool SHIFT> DI void phase_attn2(const Params& p, const Grp& G, int layer, LAS unsigned char* lds, int tid, int wave, int lane, int vcu, bool dry) {
;     ...
;                 for (int r = 0; r < 16; ++r) {
;                     float a[4]; float ss = 0.f;
; #pragma unroll
;                     for (int cb = 0; cb < 4; ++cb) { a[cb] = o[rbq][cb][r] - lamv * ex[crow(r, hiv) * 128 + 32 * cb + l31v]; ss += a[cb] * a[cb]; }
;                     ss = half_sum32(ss); const float ri = rsqrtf(ss * (1.0f / 128.0f) + EPSN);
;                     LAS bf16_t* sp = (LAS bf16_t*)(stg + crow(r, hiv) * 256) + l31v;
; #pragma unroll
;                     for (int cb = 0; cb < 4; ++cb) sp[32 * cb] = f2bf1(a[cb] * ri * sw[cb]);
	v_pk_fma_f32 v[80:81], s[30:31], v[80:81], v[86:87] op_sel_hi:[0,1,1] neg_lo:[1,0,0] neg_hi:[1,0,0]
	v_pk_mul_f32 v[86:87], v[80:81], v[80:81]
	v_mov_b32_e32 v102, v90
	v_mov_b32_e32 v103, v98
	v_mov_b32_e32 v98, v91
	v_pk_add_f32 v[90:91], v[102:103], v[98:99]
	v_mov_b32_e32 v98, v100
	v_mov_b32_e32 v99, v86
	v_pk_add_f32 v[90:91], v[90:91], v[98:99]
	v_mov_b32_e32 v86, v101
	v_pk_add_f32 v[86:87], v[90:91], v[86:87]
	v_mul_f32_e32 v98, 0x4b800000, v96
	v_cmp_gt_f32_e32 vcc, s90, v96
	ds_write_b16 v94, v97 offset:4800
	s_waitcnt lgkmcnt(1)
	s_nop 1
	v_add_f32_dpp v86, v86, v86 quad_perm:[1,0,3,2] row_mask:0xf bank_mask:0xf
	v_add_f32_dpp v87, v87, v87 quad_perm:[1,0,3,2] row_mask:0xf bank_mask:0xf
	v_cndmask_b32_e32 v96, v96, v98, vcc
	v_rsq_f32_e32 v96, v96
	s_waitcnt lgkmcnt(0)
	s_nop 1
	v_add_f32_dpp v86, v86, v86 quad_perm:[2,3,0,1] row_mask:0xf bank_mask:0xf
	v_add_f32_dpp v87, v87, v87 quad_perm:[2,3,0,1] row_mask:0xf bank_mask:0xf
	v_mul_f32_e32 v97, 0x45800000, v96
	v_cndmask_b32_e32 v96, v96, v97, vcc
	v_mul_f32_e32 v82, v82, v96
	v_mul_f32_e32 v82, v105, v82
	v_cvt_pk_bf16_f32 v82, v82, s0
	ds_write_b16 v94, v82 offset:4864
	v_mul_f32_e32 v97, v83, v96
	s_waitcnt lgkmcnt(1)
	s_nop 1
	v_add_f32_dpp v82, v86, v86 row_half_mirror row_mask:0xf bank_mask:0xf
	v_add_f32_dpp v83, v87, v87 row_half_mirror row_mask:0xf bank_mask:0xf
	v_mul_f32_e32 v74, v74, v96
	v_mul_f32_e32 v90, v104, v97
	v_mul_f32_e32 v74, v95, v74
	v_cvt_pk_bf16_f32 v90, v90, s0
	s_waitcnt lgkmcnt(0)
	s_nop 1
	v_add_f32_dpp v82, v82, v82 row_ror:8 row_mask:0xf bank_mask:0xf
	v_add_f32_dpp v83, v83, v83 row_ror:8 row_mask:0xf bank_mask:0xf
	ds_bpermute_b32 v87, v215, v83
	ds_bpermute_b32 v86, v215, v82
	v_cvt_pk_bf16_f32 v74, v74, s0
	ds_write_b16 v94, v90 offset:4928
	ds_write_b16 v94, v74 offset:4992
	v_mul_f32_e32 v90, v75, v96
	s_waitcnt lgkmcnt(2)
	v_pk_add_f32 v[74:75], v[82:83], v[86:87]
	ds_read2_b32 v[86:87], v106 offset0:192 offset1:224
	v_pk_fma_f32 v[74:75], v[74:75], s[0:1], v[78:79] op_sel_hi:[1,0,0]
	s_waitcnt lgkmcnt(0)
	v_pk_fma_f32 v[70:71], s[30:31], v[86:87], v[70:71] op_sel_hi:[0,1,1] neg_lo:[1,0,0] neg_hi:[1,0,0]
	v_mul_f32_e32 v82, 0x4b800000, v75
	v_cmp_gt_f32_e32 vcc, s90, v75
	v_pk_mul_f32 v[86:87], v[70:71], v[70:71]
	s_nop 0
	v_cndmask_b32_e32 v75, v75, v82, vcc
	v_rsq_f32_e32 v75, v75
	v_mul_f32_e32 v82, v93, v90
	v_cvt_pk_bf16_f32 v82, v82, s0
	ds_write_b16 v94, v82 offset:5056
	v_mul_f32_e32 v82, 0x45800000, v75
	v_cndmask_b32_e32 v75, v75, v82, vcc
	v_mul_f32_e32 v82, v84, v75
	v_mul_f32_e32 v82, v105, v82
	v_cvt_pk_bf16_f32 v82, v82, s0
	ds_write_b16 v94, v82 offset:6144
	v_mul_f32_e32 v82, v85, v75
	v_mul_f32_e32 v82, v104, v82
	v_cvt_pk_bf16_f32 v82, v82, s0
	ds_write_b16 v94, v82 offset:6208
	ds_read2_b32 v[82:83], v106 offset1:32
	v_mul_f32_e32 v80, v80, v75
	v_mul_f32_e32 v80, v95, v80
	v_cvt_pk_bf16_f32 v80, v80, s0
	ds_write_b16 v94, v80 offset:6272
	s_waitcnt lgkmcnt(1)
	v_pk_fma_f32 v[68:69], s[30:31], v[82:83], v[68:69] op_sel_hi:[0,1,1] neg_lo:[1,0,0] neg_hi:[1,0,0]
	ds_read2_b32 v[82:83], v106 offset0:128 offset1:160
	v_mul_f32_e32 v75, v81, v75
	ds_read2_b32 v[80:81], v106 offset0:64 offset1:96
	v_pk_mul_f32 v[84:85], v[68:69], v[68:69]
	v_mul_f32_e32 v75, v93, v75
	s_waitcnt lgkmcnt(1)
	v_pk_fma_f32 v[72:73], s[30:31], v[82:83], v[72:73] op_sel_hi:[0,1,1] neg_lo:[1,0,0] neg_hi:[1,0,0]
	v_pk_mul_f32 v[82:83], v[72:73], v[72:73]
	s_waitcnt lgkmcnt(0)
	v_pk_fma_f32 v[66:67], s[30:31], v[80:81], v[66:67] op_sel_hi:[0,1,1] neg_lo:[1,0,0] neg_hi:[1,0,0]
	v_pk_mul_f32 v[80:81], v[66:67], v[66:67]
	v_mov_b32_e32 v90, v82
	v_mov_b32_e32 v91, v84
	v_mov_b32_e32 v84, v83
	v_pk_add_f32 v[82:83], v[90:91], v[84:85]
	v_mov_b32_e32 v84, v86
	v_mov_b32_e32 v85, v80
	v_pk_add_f32 v[82:83], v[82:83], v[84:85]
	v_mov_b32_e32 v80, v87
	v_pk_add_f32 v[80:81], v[82:83], v[80:81]
	v_cvt_pk_bf16_f32 v96, v75, s0
	v_mul_f32_e32 v75, 0x4b800000, v74
	v_cmp_gt_f32_e32 vcc, s90, v74
	ds_write_b16 v94, v96 offset:6336
	s_nop 0
	v_cndmask_b32_e32 v74, v74, v75, vcc
	v_rsq_f32_e32 v84, v74
	s_waitcnt lgkmcnt(1)
	s_nop 1
	v_add_f32_dpp v74, v80, v80 quad_perm:[1,0,3,2] row_mask:0xf bank_mask:0xf
	v_add_f32_dpp v75, v81, v81 quad_perm:[1,0,3,2] row_mask:0xf bank_mask:0xf
	v_mul_f32_e32 v82, 0x45800000, v84
	v_cndmask_b32_e32 v82, v84, v82, vcc
	v_mul_f32_e32 v76, v76, v82
	v_mul_f32_e32 v76, v95, v76
	s_waitcnt lgkmcnt(0)
	s_nop 1
	v_add_f32_dpp v74, v74, v74 quad_perm:[2,3,0,1] row_mask:0xf bank_mask:0xf
	v_add_f32_dpp v75, v75, v75 quad_perm:[2,3,0,1] row_mask:0xf bank_mask:0xf
	v_cvt_pk_bf16_f32 v76, v76, s0
	ds_write_b16 v94, v76 offset:6528
	v_mul_f32_e32 v76, v77, v82
	v_mul_f32_e32 v76, v93, v76
	s_waitcnt lgkmcnt(1)
	s_nop 1
	v_add_f32_dpp v74, v74, v74 row_half_mirror row_mask:0xf bank_mask:0xf
	v_add_f32_dpp v75, v75, v75 row_half_mirror row_mask:0xf bank_mask:0xf
	v_cvt_pk_bf16_f32 v76, v76, s0
	ds_write_b16 v94, v76 offset:6592
	v_mul_f32_e32 v83, v88, v82
	v_mul_f32_e32 v83, v105, v83
	s_waitcnt lgkmcnt(1)
; #define LAS __attribute__((address_space(3)))
; DI bf16_t f2bf1(float f) { return (bf16_t)(pk2(f, 0.f) & 0xffffu); }
; DI int crow(int r, int hi) { return (r & 3) + 8 * (r >> 2) + 4 * hi; }
; template <bool SHIFT> DI void phase_attn2(const Params& p, const Grp& G, int layer, LAS unsigned char* lds, int tid, int wave, int lane, int vcu, bool dry) {
;     ...
;                 for (int r = 0; r < 16; ++r) {
;                     float a[4]; float ss = 0.f;
; #pragma unroll
;                     for (int cb = 0; cb < 4; ++cb) { a[cb] = o[rbq][cb][r] - lamv * ex[crow(r, hiv) * 128 + 32 * cb + l31v]; ss += a[cb] * a[cb]; }
;                     ss = half_sum32(ss); const float ri = rsqrtf(ss * (1.0f / 128.0f) + EPSN);
;                     LAS bf16_t* sp = (LAS bf16_t*)(stg + crow(r, hiv) * 256) + l31v;
; #pragma unroll
;                     for (int cb = 0; cb < 4; ++cb) sp[32 * cb] = f2bf1(a[cb] * ri * sw[cb]);
;                 }
;                 asm volatile("s_waitcnt lgkmcnt(0)" ::: "memory");
; #pragma unroll
;                 for (int i = 0; i < 8; ++i) { const int q = lanev + 64 * i, row = q >> 4, ch = q & 15;
;                     const u32x4 v = *(const LAS u32x4*)(stg + row * 256 + ch * 16);
;                     *(u32x4*)(obase + (size_t)(64 * qg + 32 * rbq + row) * MIXW + h * 128 + ch * 8) = v; }
	s_nop 1
	v_add_f32_dpp v74, v74, v74 row_ror:8 row_mask:0xf bank_mask:0xf
	v_add_f32_dpp v75, v75, v75 row_ror:8 row_mask:0xf bank_mask:0xf
	ds_bpermute_b32 v81, v215, v75
	ds_bpermute_b32 v80, v215, v74
	v_cvt_pk_bf16_f32 v83, v83, s0
	ds_write_b16 v94, v83 offset:6400
	v_mul_f32_e32 v83, v89, v82
	v_mul_f32_e32 v83, v104, v83
	s_waitcnt lgkmcnt(1)
	v_pk_add_f32 v[74:75], v[74:75], v[80:81]
	v_cvt_pk_bf16_f32 v83, v83, s0
	v_pk_fma_f32 v[74:75], v[74:75], s[0:1], v[78:79] op_sel_hi:[1,0,0]
	ds_write_b16 v94, v83 offset:6464
	v_mul_f32_e32 v77, 0x4b800000, v75
	v_cmp_gt_f32_e32 vcc, s90, v75
	s_nop 1
	v_cndmask_b32_e32 v75, v75, v77, vcc
	v_rsq_f32_e32 v75, v75
	s_nop 0
	v_mul_f32_e32 v76, 0x45800000, v75
	v_cndmask_b32_e32 v75, v75, v76, vcc
	v_mul_f32_e32 v66, v66, v75
	v_mul_f32_e32 v66, v95, v66
	v_cvt_pk_bf16_f32 v66, v66, s0
	ds_write_b16 v94, v66 offset:6784
	v_mul_f32_e32 v66, v67, v75
	v_mul_f32_e32 v67, 0x4b800000, v74
	v_cmp_gt_f32_e32 vcc, s90, v74
	v_mul_f32_e32 v66, v93, v66
	v_cvt_pk_bf16_f32 v66, v66, s0
	v_cndmask_b32_e32 v67, v74, v67, vcc
	v_rsq_f32_e32 v67, v67
	ds_write_b16 v94, v66 offset:6848
	v_mul_f32_e32 v68, v68, v75
	v_mul_f32_e32 v68, v105, v68
	v_mul_f32_e32 v66, 0x45800000, v67
	v_cndmask_b32_e32 v66, v67, v66, vcc
	v_mul_f32_e32 v67, v72, v66
	v_mul_f32_e32 v67, v105, v67
	v_cvt_pk_bf16_f32 v67, v67, s0
	ds_write_b16 v94, v67 offset:6912
	v_mul_f32_e32 v67, v73, v66
	v_mul_f32_e32 v67, v104, v67
	v_cvt_pk_bf16_f32 v68, v68, s0
	v_cvt_pk_bf16_f32 v67, v67, s0
	ds_write_b16 v94, v68 offset:6656
	v_mul_f32_e32 v68, v69, v75
	ds_write_b16 v94, v67 offset:6976
	v_mul_f32_e32 v67, v70, v66
	v_mul_f32_e32 v66, v71, v66
	v_mul_f32_e32 v68, v104, v68
	v_mul_f32_e32 v67, v95, v67
	v_mul_f32_e32 v66, v93, v66
	v_cvt_pk_bf16_f32 v68, v68, s0
	v_cvt_pk_bf16_f32 v67, v67, s0
	v_cvt_pk_bf16_f32 v66, v66, s0
	v_ashrrev_i32_e32 v70, 4, v128
	v_readlane_b32 s0, v254, 49
	ds_write_b16 v94, v68 offset:6720
	ds_write_b16 v94, v67 offset:7040
	ds_write_b16 v94, v66 offset:7104
	v_lshl_add_u32 v66, v70, 8, v92
	v_add_u32_e32 v70, s0, v70
	s_waitcnt lgkmcnt(0)
	v_ashrrev_i32_e32 v71, 31, v70
	ds_read_b128 v[66:69], v66
	v_lshlrev_b64 v[70:71], 11, v[70:71]
	v_lshl_add_u64 v[74:75], v[64:65], 0, v[70:71]
	v_add_u32_e32 v70, 64, v128
	v_ashrrev_i32_e32 v76, 4, v70
	v_lshl_add_u32 v70, v76, 8, v92
	ds_read_b128 v[70:73], v70
	s_waitcnt lgkmcnt(1)
	global_store_dwordx4 v[74:75], v[66:69], off
	s_nop 1
	v_add_u32_e32 v66, s0, v76
	v_ashrrev_i32_e32 v67, 31, v66
	v_lshlrev_b64 v[66:67], 11, v[66:67]
	v_lshl_add_u64 v[66:67], v[64:65], 0, v[66:67]
	s_waitcnt lgkmcnt(0)
	global_store_dwordx4 v[66:67], v[70:73], off
	v_add_u32_e32 v66, 0x80, v128
	s_nop 0
	v_ashrrev_i32_e32 v70, 4, v66
	v_lshl_add_u32 v66, v70, 8, v92
	v_add_u32_e32 v70, s0, v70
	v_ashrrev_i32_e32 v71, 31, v70
	ds_read_b128 v[66:69], v66
	v_lshlrev_b64 v[70:71], 11, v[70:71]
	v_lshl_add_u64 v[74:75], v[64:65], 0, v[70:71]
	v_add_u32_e32 v70, 0xc0, v128
	v_ashrrev_i32_e32 v76, 4, v70
	v_lshl_add_u32 v70, v76, 8, v92
	ds_read_b128 v[70:73], v70
	s_waitcnt lgkmcnt(1)
	global_store_dwordx4 v[74:75], v[66:69], off
	s_nop 1
	v_add_u32_e32 v66, s0, v76
	v_ashrrev_i32_e32 v67, 31, v66
	v_lshlrev_b64 v[66:67], 11, v[66:67]
	v_lshl_add_u64 v[66:67], v[64:65], 0, v[66:67]
	s_waitcnt lgkmcnt(0)
	global_store_dwordx4 v[66:67], v[70:73], off
	v_add_u32_e32 v66, 0x100, v128
	s_nop 0
	v_ashrrev_i32_e32 v70, 4, v66
	v_lshl_add_u32 v66, v70, 8, v92
	v_add_u32_e32 v70, s0, v70
	v_ashrrev_i32_e32 v71, 31, v70
	ds_read_b128 v[66:69], v66
	v_lshlrev_b64 v[70:71], 11, v[70:71]
	v_lshl_add_u64 v[74:75], v[64:65], 0, v[70:71]
	v_add_u32_e32 v70, 0x140, v128
	v_ashrrev_i32_e32 v76, 4, v70
	v_lshl_add_u32 v70, v76, 8, v92
	ds_read_b128 v[70:73], v70
	s_waitcnt lgkmcnt(1)
	global_store_dwordx4 v[74:75], v[66:69], off
	s_nop 1
	v_add_u32_e32 v66, s0, v76
	v_ashrrev_i32_e32 v67, 31, v66
	v_lshlrev_b64 v[66:67], 11, v[66:67]
	v_lshl_add_u64 v[66:67], v[64:65], 0, v[66:67]
	s_waitcnt lgkmcnt(0)
	global_store_dwordx4 v[66:67], v[70:73], off
	v_add_u32_e32 v66, 0x180, v128
	s_nop 0
	v_ashrrev_i32_e32 v70, 4, v66
	v_lshl_add_u32 v66, v70, 8, v92
	v_add_u32_e32 v70, s0, v70
	v_ashrrev_i32_e32 v71, 31, v70
	ds_read_b128 v[66:69], v66
	v_lshlrev_b64 v[70:71], 11, v[70:71]
	v_lshl_add_u64 v[74:75], v[64:65], 0, v[70:71]
	v_add_u32_e32 v70, 0x1c0, v128
	v_ashrrev_i32_e32 v76, 4, v70
	v_lshl_add_u32 v70, v76, 8, v92
	ds_read_b128 v[70:73], v70
	s_waitcnt lgkmcnt(1)
	global_store_dwordx4 v[74:75], v[66:69], off
	s_nop 1
	v_add_u32_e32 v66, s0, v76
	v_ashrrev_i32_e32 v67, 31, v66
	v_lshlrev_b64 v[66:67], 11, v[66:67]
	v_lshl_add_u64 v[66:67], v[64:65], 0, v[66:67]
	s_waitcnt lgkmcnt(0)
	global_store_dwordx4 v[66:67], v[70:73], off
	s_waitcnt lgkmcnt(0)

; #define LAS __attribute__((address_space(3)))
; DI bf16_t f2bf1(float f) { return (bf16_t)(pk2(f, 0.f) & 0xffffu); }
; DI int crow(int r, int hi) { return (r & 3) + 8 * (r >> 2) + 4 * hi; }
; template <bool SHIFT> DI void phase_attn2(const Params& p, const Grp& G, int layer, LAS unsigned char* lds, int tid, int wave, int lane, int vcu, bool dry) {
;     ...
;         for (int rbq = 0; rbq < 2; ++rbq) {
; #pragma unroll
;             for (int r = 0; r < 16; ++r) { const float rl = __builtin_amdgcn_rcpf(lscr[32 * rbq + crow(r, hiv)]);
; #pragma unroll
;                 for (int cb = 0; cb < 4; ++cb) o[rbq][cb][r] *= rl; }
;             if (c == 1) {
; #pragma unroll
;                 for (int cb = 0; cb < 4; ++cb)
; #pragma unroll
;                     for (int r = 0; r < 16; ++r) ex[crow(r, hiv) * 128 + 32 * cb + l31v] = o[rbq][cb][r];
;             }
;             __syncthreads();
;             if (c == 0) {
;                 LAS unsigned char* stg = lds + AT2_QS + wave * 8192;
; #pragma unroll
;                 for (int r = 0; r < 16; ++r) {
;                     float a[4]; float ss = 0.f;
; #pragma unroll
;                     for (int cb = 0; cb < 4; ++cb) { a[cb] = o[rbq][cb][r] - lamv * ex[crow(r, hiv) * 128 + 32 * cb + l31v]; ss += a[cb] * a[cb]; }
;                     ss = half_sum32(ss); const float ri = rsqrtf(ss * (1.0f / 128.0f) + EPSN);
;                     LAS bf16_t* sp = (LAS bf16_t*)(stg + crow(r, hiv) * 256) + l31v;
; #pragma unroll
;                     for (int cb = 0; cb < 4; ++cb) sp[32 * cb] = f2bf1(a[cb] * ri * sw[cb]);
.LBB0_396:
	s_and_b64 vcc, exec, s[40:41]
	s_waitcnt lgkmcnt(0)
	s_barrier
	s_cbranch_vccnz .LBB0_376
	ds_read2_b32 v[8:9], v129 offset1:32
	ds_read2_b32 v[14:15], v129 offset0:64 offset1:96
	ds_read2_b32 v[26:27], v129 offset0:128 offset1:160
	ds_read2_b32 v[28:29], v129 offset0:192 offset1:224
	s_mov_b32 s0, 0x358637bd
	s_waitcnt lgkmcnt(3)
	v_pk_fma_f32 v[30:31], s[30:31], v[8:9], v[84:85] op_sel_hi:[0,1,1] neg_lo:[1,0,0] neg_hi:[1,0,0]
	s_waitcnt lgkmcnt(2)
	v_pk_fma_f32 v[14:15], s[30:31], v[14:15], v[86:87] op_sel_hi:[0,1,1] neg_lo:[1,0,0] neg_hi:[1,0,0]
	s_waitcnt lgkmcnt(1)
	v_pk_fma_f32 v[26:27], s[30:31], v[26:27], v[88:89] op_sel_hi:[0,1,1] neg_lo:[1,0,0] neg_hi:[1,0,0]
	v_pk_mul_f32 v[8:9], v[30:31], v[30:31]
	v_pk_mul_f32 v[42:43], v[26:27], v[26:27]
	s_waitcnt lgkmcnt(0)
	v_pk_fma_f32 v[28:29], s[30:31], v[28:29], v[90:91] op_sel_hi:[0,1,1] neg_lo:[1,0,0] neg_hi:[1,0,0]
	v_pk_mul_f32 v[40:41], v[14:15], v[14:15]
	v_pk_mul_f32 v[44:45], v[28:29], v[28:29]
	v_mov_b32_e32 v46, v42
	v_mov_b32_e32 v47, v8
	v_mov_b32_e32 v8, v43
	v_pk_add_f32 v[8:9], v[46:47], v[8:9]
	v_mov_b32_e32 v42, v44
	v_mov_b32_e32 v43, v40
	v_pk_add_f32 v[8:9], v[8:9], v[42:43]
	v_mov_b32_e32 v40, v45
	v_pk_add_f32 v[8:9], v[8:9], v[40:41]
	s_waitcnt lgkmcnt(0)
	s_nop 1
	v_add_f32_dpp v8, v8, v8 quad_perm:[1,0,3,2] row_mask:0xf bank_mask:0xf
	v_add_f32_dpp v9, v9, v9 quad_perm:[1,0,3,2] row_mask:0xf bank_mask:0xf
	s_waitcnt lgkmcnt(0)
	s_nop 1
	v_add_f32_dpp v8, v8, v8 quad_perm:[2,3,0,1] row_mask:0xf bank_mask:0xf
	v_add_f32_dpp v9, v9, v9 quad_perm:[2,3,0,1] row_mask:0xf bank_mask:0xf
	s_waitcnt lgkmcnt(0)
	s_nop 1
	v_add_f32_dpp v8, v8, v8 row_half_mirror row_mask:0xf bank_mask:0xf
	v_add_f32_dpp v9, v9, v9 row_half_mirror row_mask:0xf bank_mask:0xf
	s_waitcnt lgkmcnt(0)
	s_nop 1
	v_add_f32_dpp v40, v8, v8 row_ror:8 row_mask:0xf bank_mask:0xf
	v_add_f32_dpp v41, v9, v9 row_ror:8 row_mask:0xf bank_mask:0xf
	ds_bpermute_b32 v43, v215, v41
	ds_bpermute_b32 v42, v215, v40
	v_mov_b64_e32 v[8:9], s[0:1]
	s_brev_b32 s0, 60
	s_waitcnt lgkmcnt(0)
	v_pk_add_f32 v[40:41], v[40:41], v[42:43]
	s_nop 0
	v_pk_fma_f32 v[40:41], v[40:41], s[0:1], v[8:9] op_sel_hi:[1,0,0]
	s_nop 0
	v_mul_f32_e32 v42, 0x4b800000, v41
	v_cmp_gt_f32_e32 vcc, s90, v41
	s_nop 1
	v_cndmask_b32_e32 v41, v41, v42, vcc
	v_rsq_f32_e32 v41, v41
	s_nop 0
	v_mul_f32_e32 v42, 0x45800000, v41
	v_cndmask_b32_e32 v41, v41, v42, vcc
	v_mul_f32_e32 v30, v30, v41
	v_mul_f32_e32 v14, v14, v41
	v_mul_f32_e32 v31, v31, v41
	v_mul_f32_e32 v30, v105, v30
	v_mul_f32_e32 v14, v95, v14
	v_mul_f32_e32 v31, v104, v31
	v_cvt_pk_bf16_f32 v30, v30, s0
	v_cvt_pk_bf16_f32 v14, v14, s0
	v_cvt_pk_bf16_f32 v31, v31, s0
	ds_write_b16 v94, v30
	ds_write_b16 v94, v31 offset:64
	ds_write_b16 v94, v14 offset:128
	v_mul_f32_e32 v14, v15, v41
	ds_read2_b32 v[30:31], v118 offset1:32
	v_mul_f32_e32 v14, v93, v14
	ds_read2_b32 v[42:43], v118 offset0:128 offset1:160
	v_cvt_pk_bf16_f32 v84, v14, s0
	ds_read2_b32 v[14:15], v118 offset0:64 offset1:96
	ds_read2_b32 v[46:47], v118 offset0:192 offset1:224
	s_waitcnt lgkmcnt(3)
	v_pk_fma_f32 v[30:31], s[30:31], v[30:31], v[82:83] op_sel_hi:[0,1,1] neg_lo:[1,0,0] neg_hi:[1,0,0]
	s_waitcnt lgkmcnt(2)
	v_pk_fma_f32 v[42:43], s[30:31], v[42:43], v[78:79] op_sel_hi:[0,1,1] neg_lo:[1,0,0] neg_hi:[1,0,0]
	v_pk_mul_f32 v[44:45], v[30:31], v[30:31]
	s_waitcnt lgkmcnt(1)
	v_pk_fma_f32 v[14:15], s[30:31], v[14:15], v[76:77] op_sel_hi:[0,1,1] neg_lo:[1,0,0] neg_hi:[1,0,0]
	v_pk_mul_f32 v[58:59], v[42:43], v[42:43]
	s_waitcnt lgkmcnt(0)
	v_pk_fma_f32 v[46:47], s[30:31], v[46:47], v[80:81] op_sel_hi:[0,1,1] neg_lo:[1,0,0] neg_hi:[1,0,0]
	v_pk_mul_f32 v[56:57], v[14:15], v[14:15]
	v_pk_mul_f32 v[60:61], v[46:47], v[46:47]
	v_mov_b32_e32 v62, v58
	v_mov_b32_e32 v63, v44
	v_mov_b32_e32 v44, v59
	v_pk_add_f32 v[44:45], v[62:63], v[44:45]
	v_mov_b32_e32 v58, v60
	v_mov_b32_e32 v59, v56
	v_pk_add_f32 v[44:45], v[44:45], v[58:59]
	v_mov_b32_e32 v56, v61
	v_pk_add_f32 v[44:45], v[44:45], v[56:57]
	v_mul_f32_e32 v41, 0x4b800000, v40
	v_cmp_gt_f32_e32 vcc, s90, v40
	ds_write_b16 v94, v84 offset:192
	s_nop 0
	v_cndmask_b32_e32 v40, v40, v41, vcc
	v_rsq_f32_e32 v58, v40
	s_waitcnt lgkmcnt(1)
	s_nop 1
	v_add_f32_dpp v40, v44, v44 quad_perm:[1,0,3,2] row_mask:0xf bank_mask:0xf
	v_add_f32_dpp v41, v45, v45 quad_perm:[1,0,3,2] row_mask:0xf bank_mask:0xf
	v_mul_f32_e32 v56, 0x45800000, v58
	v_cndmask_b32_e32 v56, v58, v56, vcc
	v_mul_f32_e32 v26, v26, v56
	v_mul_f32_e32 v26, v105, v26
	s_waitcnt lgkmcnt(0)
	s_nop 1
	v_add_f32_dpp v40, v40, v40 quad_perm:[2,3,0,1] row_mask:0xf bank_mask:0xf
	v_add_f32_dpp v41, v41, v41 quad_perm:[2,3,0,1] row_mask:0xf bank_mask:0xf
	v_cvt_pk_bf16_f32 v26, v26, s0
	ds_write_b16 v94, v26 offset:256
	v_mul_f32_e32 v57, v27, v56
	v_mul_f32_e32 v28, v28, v56
	s_waitcnt lgkmcnt(1)
	s_nop 1
	v_add_f32_dpp v26, v40, v40 row_half_mirror row_mask:0xf bank_mask:0xf
	v_add_f32_dpp v27, v41, v41 row_half_mirror row_mask:0xf bank_mask:0xf
	v_mul_f32_e32 v28, v95, v28
	v_cvt_pk_bf16_f32 v28, v28, s0
	ds_write_b16 v94, v28 offset:384
	v_mul_f32_e32 v28, v29, v56
	s_waitcnt lgkmcnt(1)
	s_nop 1
	v_add_f32_dpp v26, v26, v26 row_ror:8 row_mask:0xf bank_mask:0xf
	v_add_f32_dpp v27, v27, v27 row_ror:8 row_mask:0xf bank_mask:0xf
	ds_bpermute_b32 v41, v215, v27
	ds_bpermute_b32 v40, v215, v26
	v_mul_f32_e32 v28, v93, v28
	v_cvt_pk_bf16_f32 v28, v28, s0
	ds_write_b16 v94, v28 offset:448
	v_mul_f32_e32 v44, v104, v57
	s_waitcnt lgkmcnt(1)
	v_pk_add_f32 v[26:27], v[26:27], v[40:41]
	v_cvt_pk_bf16_f32 v44, v44, s0
	v_pk_fma_f32 v[26:27], v[26:27], s[0:1], v[8:9] op_sel_hi:[1,0,0]
	ds_write_b16 v94, v44 offset:320
	v_mul_f32_e32 v29, 0x4b800000, v27
	v_cmp_gt_f32_e32 vcc, s90, v27
	ds_read2_b32 v[44:45], v111 offset0:192 offset1:224
	s_waitcnt lgkmcnt(0)
; #define LAS __attribute__((address_space(3)))
; DI bf16_t f2bf1(float f) { return (bf16_t)(pk2(f, 0.f) & 0xffffu); }
; DI int crow(int r, int hi) { return (r & 3) + 8 * (r >> 2) + 4 * hi; }
; template <bool SHIFT> DI void phase_attn2(const Params& p, const Grp& G, int layer, LAS unsigned char* lds, int tid, int wave, int lane, int vcu, bool dry) {
;     ...
;                 for (int r = 0; r < 16; ++r) {
;                     float a[4]; float ss = 0.f;
; #pragma unroll
;                     for (int cb = 0; cb < 4; ++cb) { a[cb] = o[rbq][cb][r] - lamv * ex[crow(r, hiv) * 128 + 32 * cb + l31v]; ss += a[cb] * a[cb]; }
;                     ss = half_sum32(ss); const float ri = rsqrtf(ss * (1.0f / 128.0f) + EPSN);
;                     LAS bf16_t* sp = (LAS bf16_t*)(stg + crow(r, hiv) * 256) + l31v;
; #pragma unroll
;                     for (int cb = 0; cb < 4; ++cb) sp[32 * cb] = f2bf1(a[cb] * ri * sw[cb]);
;                 }
	v_pk_fma_f32 v[44:45], s[30:31], v[44:45], v[72:73] op_sel_hi:[0,1,1] neg_lo:[1,0,0] neg_hi:[1,0,0]
	v_cndmask_b32_e32 v27, v27, v29, vcc
	v_rsq_f32_e32 v27, v27
	v_pk_mul_f32 v[60:61], v[44:45], v[44:45]
	v_mul_f32_e32 v28, 0x45800000, v27
	v_cndmask_b32_e32 v27, v27, v28, vcc
	v_mul_f32_e32 v28, v30, v27
	v_mul_f32_e32 v28, v105, v28
	v_cvt_pk_bf16_f32 v28, v28, s0
	v_mul_f32_e32 v14, v14, v27
	ds_write_b16 v94, v28 offset:512
	v_mul_f32_e32 v28, v31, v27
	v_mul_f32_e32 v14, v95, v14
	v_mul_f32_e32 v28, v104, v28
	v_cvt_pk_bf16_f32 v14, v14, s0
	v_cvt_pk_bf16_f32 v28, v28, s0
	ds_write_b16 v94, v14 offset:640
	v_mul_f32_e32 v14, v15, v27
	ds_write_b16 v94, v28 offset:576
	ds_read2_b32 v[28:29], v111 offset1:32
	v_mul_f32_e32 v14, v93, v14
	ds_read2_b32 v[30:31], v111 offset0:128 offset1:160
	v_cvt_pk_bf16_f32 v76, v14, s0
	ds_read2_b32 v[14:15], v111 offset0:64 offset1:96
	s_waitcnt lgkmcnt(2)
	v_pk_fma_f32 v[28:29], s[30:31], v[28:29], v[74:75] op_sel_hi:[0,1,1] neg_lo:[1,0,0] neg_hi:[1,0,0]
	v_pk_mul_f32 v[40:41], v[28:29], v[28:29]
	s_waitcnt lgkmcnt(1)
	v_pk_fma_f32 v[30:31], s[30:31], v[30:31], v[70:71] op_sel_hi:[0,1,1] neg_lo:[1,0,0] neg_hi:[1,0,0]
	v_pk_mul_f32 v[58:59], v[30:31], v[30:31]
	s_waitcnt lgkmcnt(0)
	v_pk_fma_f32 v[14:15], s[30:31], v[14:15], v[68:69] op_sel_hi:[0,1,1] neg_lo:[1,0,0] neg_hi:[1,0,0]
	v_pk_mul_f32 v[56:57], v[14:15], v[14:15]
	v_mov_b32_e32 v62, v58
	v_mov_b32_e32 v63, v40
	v_mov_b32_e32 v40, v59
	v_pk_add_f32 v[40:41], v[62:63], v[40:41]
	v_mov_b32_e32 v58, v60
	v_mov_b32_e32 v59, v56
	v_pk_add_f32 v[40:41], v[40:41], v[58:59]
	v_mov_b32_e32 v56, v61
	v_pk_add_f32 v[40:41], v[40:41], v[56:57]
	v_mul_f32_e32 v27, 0x4b800000, v26
	v_cmp_gt_f32_e32 vcc, s90, v26
	ds_write_b16 v94, v76 offset:704
	s_nop 0
	v_cndmask_b32_e32 v26, v26, v27, vcc
	v_rsq_f32_e32 v58, v26
	s_waitcnt lgkmcnt(1)
	s_nop 1
	v_add_f32_dpp v26, v40, v40 quad_perm:[1,0,3,2] row_mask:0xf bank_mask:0xf
	v_add_f32_dpp v27, v41, v41 quad_perm:[1,0,3,2] row_mask:0xf bank_mask:0xf
	v_mul_f32_e32 v56, 0x45800000, v58
	v_cndmask_b32_e32 v56, v58, v56, vcc
	v_mul_f32_e32 v42, v42, v56
	v_mul_f32_e32 v42, v105, v42
	s_waitcnt lgkmcnt(0)
	s_nop 1
	v_add_f32_dpp v26, v26, v26 quad_perm:[2,3,0,1] row_mask:0xf bank_mask:0xf
	v_add_f32_dpp v27, v27, v27 quad_perm:[2,3,0,1] row_mask:0xf bank_mask:0xf
	v_cvt_pk_bf16_f32 v42, v42, s0
	ds_write_b16 v94, v42 offset:768
	v_mul_f32_e32 v42, v43, v56
	v_mul_f32_e32 v42, v104, v42
	s_waitcnt lgkmcnt(1)
	s_nop 1
	v_add_f32_dpp v26, v26, v26 row_half_mirror row_mask:0xf bank_mask:0xf
	v_add_f32_dpp v27, v27, v27 row_half_mirror row_mask:0xf bank_mask:0xf
	v_cvt_pk_bf16_f32 v42, v42, s0
	ds_write_b16 v94, v42 offset:832
	v_mul_f32_e32 v42, v46, v56
	v_mul_f32_e32 v42, v95, v42
	s_waitcnt lgkmcnt(1)
	s_nop 1
	v_add_f32_dpp v26, v26, v26 row_ror:8 row_mask:0xf bank_mask:0xf
	v_add_f32_dpp v27, v27, v27 row_ror:8 row_mask:0xf bank_mask:0xf
	ds_bpermute_b32 v41, v215, v27
	ds_bpermute_b32 v40, v215, v26
	v_cvt_pk_bf16_f32 v42, v42, s0
	ds_write_b16 v94, v42 offset:896
	v_mul_f32_e32 v42, v47, v56
	ds_read2_b32 v[46:47], v110 offset0:192 offset1:224
	s_waitcnt lgkmcnt(2)
	v_pk_add_f32 v[26:27], v[26:27], v[40:41]
	s_waitcnt lgkmcnt(0)
	v_pk_fma_f32 v[46:47], s[30:31], v[46:47], v[54:55] op_sel_hi:[0,1,1] neg_lo:[1,0,0] neg_hi:[1,0,0]
	v_pk_fma_f32 v[26:27], v[26:27], s[0:1], v[8:9] op_sel_hi:[1,0,0]
	v_pk_mul_f32 v[54:55], v[46:47], v[46:47]
	v_mul_f32_e32 v40, 0x4b800000, v27
	v_cmp_gt_f32_e32 vcc, s90, v27
	s_nop 1
	v_cndmask_b32_e32 v27, v27, v40, vcc
	v_rsq_f32_e32 v27, v27
	v_mul_f32_e32 v40, v93, v42
	v_cvt_pk_bf16_f32 v40, v40, s0
	ds_write_b16 v94, v40 offset:960
	v_mul_f32_e32 v40, 0x45800000, v27
	v_cndmask_b32_e32 v27, v27, v40, vcc
	v_mul_f32_e32 v28, v28, v27
	v_mul_f32_e32 v28, v105, v28
	v_cvt_pk_bf16_f32 v28, v28, s0
	v_mul_f32_e32 v14, v14, v27
	ds_write_b16 v94, v28 offset:2048
	v_mul_f32_e32 v28, v29, v27
	v_mul_f32_e32 v14, v95, v14
	v_mul_f32_e32 v28, v104, v28
	v_cvt_pk_bf16_f32 v14, v14, s0
	v_cvt_pk_bf16_f32 v28, v28, s0
	ds_write_b16 v94, v14 offset:2176
	v_mul_f32_e32 v14, v15, v27
	ds_write_b16 v94, v28 offset:2112
	ds_read2_b32 v[28:29], v110 offset1:32
	v_mul_f32_e32 v14, v93, v14
	ds_read2_b32 v[40:41], v110 offset0:128 offset1:160
	v_cvt_pk_bf16_f32 v58, v14, s0
	ds_read2_b32 v[14:15], v110 offset0:64 offset1:96
	s_waitcnt lgkmcnt(2)
	v_pk_fma_f32 v[28:29], s[30:31], v[28:29], v[52:53] op_sel_hi:[0,1,1] neg_lo:[1,0,0] neg_hi:[1,0,0]
	v_pk_mul_f32 v[42:43], v[28:29], v[28:29]
	s_waitcnt lgkmcnt(1)
	v_pk_fma_f32 v[40:41], s[30:31], v[40:41], v[66:67] op_sel_hi:[0,1,1] neg_lo:[1,0,0] neg_hi:[1,0,0]
	v_pk_mul_f32 v[52:53], v[40:41], v[40:41]
	s_waitcnt lgkmcnt(0)
	v_pk_fma_f32 v[14:15], s[30:31], v[14:15], v[50:51] op_sel_hi:[0,1,1] neg_lo:[1,0,0] neg_hi:[1,0,0]
	v_pk_mul_f32 v[50:51], v[14:15], v[14:15]
	v_mov_b32_e32 v56, v52
	v_mov_b32_e32 v57, v42
	v_mov_b32_e32 v42, v53
	v_pk_add_f32 v[42:43], v[56:57], v[42:43]
	v_mov_b32_e32 v52, v54
	v_mov_b32_e32 v53, v50
	v_pk_add_f32 v[42:43], v[42:43], v[52:53]
	v_mov_b32_e32 v50, v55
	v_pk_add_f32 v[42:43], v[42:43], v[50:51]
	v_mul_f32_e32 v27, 0x4b800000, v26
	v_cmp_gt_f32_e32 vcc, s90, v26
	ds_write_b16 v94, v58 offset:2240
	s_nop 0
	v_cndmask_b32_e32 v26, v26, v27, vcc
	v_rsq_f32_e32 v52, v26
	s_waitcnt lgkmcnt(1)
	s_nop 1
	v_add_f32_dpp v26, v42, v42 quad_perm:[1,0,3,2] row_mask:0xf bank_mask:0xf
	v_add_f32_dpp v27, v43, v43 quad_perm:[1,0,3,2] row_mask:0xf bank_mask:0xf
	v_mul_f32_e32 v50, 0x45800000, v52
	v_cndmask_b32_e32 v50, v52, v50, vcc
	v_mul_f32_e32 v30, v30, v50
	v_mul_f32_e32 v30, v105, v30
	s_waitcnt lgkmcnt(0)
; #define LAS __attribute__((address_space(3)))
; DI bf16_t f2bf1(float f) { return (bf16_t)(pk2(f, 0.f) & 0xffffu); }
; DI int crow(int r, int hi) { return (r & 3) + 8 * (r >> 2) + 4 * hi; }
; template <bool SHIFT> DI void phase_attn2(const Params& p, const Grp& G, int layer, LAS unsigned char* lds, int tid, int wave, int lane, int vcu, bool dry) {
;     ...
;                 for (int r = 0; r < 16; ++r) {
;                     float a[4]; float ss = 0.f;
; #pragma unroll
;                     for (int cb = 0; cb < 4; ++cb) { a[cb] = o[rbq][cb][r] - lamv * ex[crow(r, hiv) * 128 + 32 * cb + l31v]; ss += a[cb] * a[cb]; }
;                     ss = half_sum32(ss); const float ri = rsqrtf(ss * (1.0f / 128.0f) + EPSN);
;                     LAS bf16_t* sp = (LAS bf16_t*)(stg + crow(r, hiv) * 256) + l31v;
; #pragma unroll
;                     for (int cb = 0; cb < 4; ++cb) sp[32 * cb] = f2bf1(a[cb] * ri * sw[cb]);
;                 }
	s_nop 1
	v_add_f32_dpp v26, v26, v26 quad_perm:[2,3,0,1] row_mask:0xf bank_mask:0xf
	v_add_f32_dpp v27, v27, v27 quad_perm:[2,3,0,1] row_mask:0xf bank_mask:0xf
	v_cvt_pk_bf16_f32 v30, v30, s0
	ds_write_b16 v94, v30 offset:2304
	v_mul_f32_e32 v51, v31, v50
	s_waitcnt lgkmcnt(1)
	s_nop 1
	v_add_f32_dpp v26, v26, v26 row_half_mirror row_mask:0xf bank_mask:0xf
	v_add_f32_dpp v27, v27, v27 row_half_mirror row_mask:0xf bank_mask:0xf
	v_mul_f32_e32 v42, v104, v51
	v_cvt_pk_bf16_f32 v42, v42, s0
	ds_write_b16 v94, v42 offset:2368
	v_mul_f32_e32 v42, v44, v50
	s_waitcnt lgkmcnt(1)
	s_nop 1
	v_add_f32_dpp v26, v26, v26 row_ror:8 row_mask:0xf bank_mask:0xf
	v_add_f32_dpp v27, v27, v27 row_ror:8 row_mask:0xf bank_mask:0xf
	ds_bpermute_b32 v31, v215, v27
	ds_bpermute_b32 v30, v215, v26
	v_mul_f32_e32 v42, v95, v42
	v_cvt_pk_bf16_f32 v42, v42, s0
	ds_write_b16 v94, v42 offset:2432
	v_mul_f32_e32 v42, v45, v50
	s_waitcnt lgkmcnt(1)
	v_pk_add_f32 v[26:27], v[26:27], v[30:31]
	ds_read2_b32 v[44:45], v109 offset0:192 offset1:224
	v_pk_fma_f32 v[26:27], v[26:27], s[0:1], v[8:9] op_sel_hi:[1,0,0]
	s_waitcnt lgkmcnt(0)
	v_pk_fma_f32 v[34:35], s[30:31], v[44:45], v[34:35] op_sel_hi:[0,1,1] neg_lo:[1,0,0] neg_hi:[1,0,0]
	v_mul_f32_e32 v30, 0x4b800000, v27
	v_cmp_gt_f32_e32 vcc, s90, v27
	v_pk_mul_f32 v[44:45], v[34:35], v[34:35]
	s_nop 0
	v_cndmask_b32_e32 v27, v27, v30, vcc
	v_rsq_f32_e32 v27, v27
	v_mul_f32_e32 v30, v93, v42
	v_cvt_pk_bf16_f32 v30, v30, s0
	ds_write_b16 v94, v30 offset:2496
	v_mul_f32_e32 v30, 0x45800000, v27
	v_cndmask_b32_e32 v27, v27, v30, vcc
	v_mul_f32_e32 v28, v28, v27
	v_mul_f32_e32 v28, v105, v28
	v_cvt_pk_bf16_f32 v28, v28, s0
	v_mul_f32_e32 v14, v14, v27
	ds_write_b16 v94, v28 offset:2560
	v_mul_f32_e32 v28, v29, v27
	v_mul_f32_e32 v14, v95, v14
	v_mul_f32_e32 v28, v104, v28
	v_cvt_pk_bf16_f32 v14, v14, s0
	v_cvt_pk_bf16_f32 v28, v28, s0
	ds_write_b16 v94, v14 offset:2688
	v_mul_f32_e32 v14, v15, v27
	ds_write_b16 v94, v28 offset:2624
	ds_read2_b32 v[28:29], v109 offset1:32
	v_mul_f32_e32 v14, v93, v14
	ds_read2_b32 v[30:31], v109 offset0:128 offset1:160
	v_cvt_pk_bf16_f32 v50, v14, s0
	ds_read2_b32 v[14:15], v109 offset0:64 offset1:96
	s_waitcnt lgkmcnt(2)
	v_pk_fma_f32 v[28:29], s[30:31], v[28:29], v[48:49] op_sel_hi:[0,1,1] neg_lo:[1,0,0] neg_hi:[1,0,0]
	v_pk_mul_f32 v[42:43], v[28:29], v[28:29]
	s_waitcnt lgkmcnt(1)
	v_pk_fma_f32 v[30:31], s[30:31], v[30:31], v[38:39] op_sel_hi:[0,1,1] neg_lo:[1,0,0] neg_hi:[1,0,0]
	v_pk_mul_f32 v[38:39], v[30:31], v[30:31]
	s_waitcnt lgkmcnt(0)
	v_pk_fma_f32 v[14:15], s[30:31], v[14:15], v[36:37] op_sel_hi:[0,1,1] neg_lo:[1,0,0] neg_hi:[1,0,0]
	v_pk_mul_f32 v[36:37], v[14:15], v[14:15]
	v_mov_b32_e32 v48, v38
	v_mov_b32_e32 v49, v42
	v_mov_b32_e32 v42, v39
	v_pk_add_f32 v[38:39], v[48:49], v[42:43]
	v_mov_b32_e32 v42, v44
	v_mov_b32_e32 v43, v36
	v_pk_add_f32 v[38:39], v[38:39], v[42:43]
	v_mov_b32_e32 v36, v45
	v_pk_add_f32 v[36:37], v[38:39], v[36:37]
	v_mul_f32_e32 v27, 0x4b800000, v26
	v_cmp_gt_f32_e32 vcc, s90, v26
	ds_write_b16 v94, v50 offset:2752
	s_nop 0
	v_cndmask_b32_e32 v26, v26, v27, vcc
	v_rsq_f32_e32 v42, v26
	s_waitcnt lgkmcnt(1)
	s_nop 1
	v_add_f32_dpp v26, v36, v36 quad_perm:[1,0,3,2] row_mask:0xf bank_mask:0xf
	v_add_f32_dpp v27, v37, v37 quad_perm:[1,0,3,2] row_mask:0xf bank_mask:0xf
	v_mul_f32_e32 v38, 0x45800000, v42
	v_cndmask_b32_e32 v38, v42, v38, vcc
	v_mul_f32_e32 v39, v40, v38
	v_mul_f32_e32 v39, v105, v39
	s_waitcnt lgkmcnt(0)
	s_nop 1
	v_add_f32_dpp v26, v26, v26 quad_perm:[2,3,0,1] row_mask:0xf bank_mask:0xf
	v_add_f32_dpp v27, v27, v27 quad_perm:[2,3,0,1] row_mask:0xf bank_mask:0xf
	v_cvt_pk_bf16_f32 v39, v39, s0
	ds_write_b16 v94, v39 offset:2816
	v_mul_f32_e32 v39, v41, v38
	v_mul_f32_e32 v39, v104, v39
	s_waitcnt lgkmcnt(1)
	s_nop 1
	v_add_f32_dpp v26, v26, v26 row_half_mirror row_mask:0xf bank_mask:0xf
	v_add_f32_dpp v27, v27, v27 row_half_mirror row_mask:0xf bank_mask:0xf
	v_cvt_pk_bf16_f32 v39, v39, s0
	ds_write_b16 v94, v39 offset:2880
	v_mul_f32_e32 v39, v46, v38
	v_mul_f32_e32 v38, v47, v38
	s_waitcnt lgkmcnt(1)
	s_nop 1
	v_add_f32_dpp v26, v26, v26 row_ror:8 row_mask:0xf bank_mask:0xf
	v_add_f32_dpp v27, v27, v27 row_ror:8 row_mask:0xf bank_mask:0xf
	ds_bpermute_b32 v37, v215, v27
	ds_bpermute_b32 v36, v215, v26
	v_mul_f32_e32 v39, v95, v39
	v_cvt_pk_bf16_f32 v39, v39, s0
	ds_write_b16 v94, v39 offset:2944
	s_waitcnt lgkmcnt(1)
	v_pk_add_f32 v[26:27], v[26:27], v[36:37]
	s_nop 0
	v_pk_fma_f32 v[26:27], v[26:27], s[0:1], v[8:9] op_sel_hi:[1,0,0]
	s_nop 0
	v_mul_f32_e32 v36, 0x4b800000, v27
	v_cmp_gt_f32_e32 vcc, s90, v27
	s_nop 1
	v_cndmask_b32_e32 v27, v27, v36, vcc
	v_rsq_f32_e32 v27, v27
	v_mul_f32_e32 v36, v93, v38
	v_cvt_pk_bf16_f32 v36, v36, s0
	ds_write_b16 v94, v36 offset:3008
	v_mul_f32_e32 v36, 0x45800000, v27
	v_cndmask_b32_e32 v27, v27, v36, vcc
	v_mul_f32_e32 v28, v28, v27
	v_mul_f32_e32 v28, v105, v28
	v_cvt_pk_bf16_f32 v28, v28, s0
	ds_write_b16 v94, v28 offset:4096
	v_mul_f32_e32 v28, v29, v27
	v_mul_f32_e32 v28, v104, v28
	v_cvt_pk_bf16_f32 v28, v28, s0
	ds_write_b16 v94, v28 offset:4160
	ds_read2_b32 v[28:29], v108 offset1:32
	v_mul_f32_e32 v14, v14, v27
	v_mul_f32_e32 v14, v95, v14
	v_cvt_pk_bf16_f32 v14, v14, s0
	ds_write_b16 v94, v14 offset:4224
	v_mul_f32_e32 v14, v15, v27
	v_mul_f32_e32 v14, v93, v14
	s_waitcnt lgkmcnt(1)
	v_pk_fma_f32 v[28:29], s[30:31], v[28:29], v[32:33] op_sel_hi:[0,1,1] neg_lo:[1,0,0] neg_hi:[1,0,0]
	ds_read2_b32 v[32:33], v108 offset0:128 offset1:160
	v_cvt_pk_bf16_f32 v42, v14, s0
	ds_read2_b32 v[14:15], v108 offset0:64 offset1:96
	ds_read2_b32 v[38:39], v108 offset0:192 offset1:224
	v_pk_mul_f32 v[36:37], v[28:29], v[28:29]
	s_waitcnt lgkmcnt(2)
; #define LAS __attribute__((address_space(3)))
; DI bf16_t f2bf1(float f) { return (bf16_t)(pk2(f, 0.f) & 0xffffu); }
; DI int crow(int r, int hi) { return (r & 3) + 8 * (r >> 2) + 4 * hi; }
; template <bool SHIFT> DI void phase_attn2(const Params& p, const Grp& G, int layer, LAS unsigned char* lds, int tid, int wave, int lane, int vcu, bool dry) {
;     ...
;                 for (int r = 0; r < 16; ++r) {
;                     float a[4]; float ss = 0.f;
; #pragma unroll
;                     for (int cb = 0; cb < 4; ++cb) { a[cb] = o[rbq][cb][r] - lamv * ex[crow(r, hiv) * 128 + 32 * cb + l31v]; ss += a[cb] * a[cb]; }
;                     ss = half_sum32(ss); const float ri = rsqrtf(ss * (1.0f / 128.0f) + EPSN);
;                     LAS bf16_t* sp = (LAS bf16_t*)(stg + crow(r, hiv) * 256) + l31v;
; #pragma unroll
;                     for (int cb = 0; cb < 4; ++cb) sp[32 * cb] = f2bf1(a[cb] * ri * sw[cb]);
;                 }
	v_pk_fma_f32 v[24:25], s[30:31], v[32:33], v[24:25] op_sel_hi:[0,1,1] neg_lo:[1,0,0] neg_hi:[1,0,0]
	v_pk_mul_f32 v[32:33], v[24:25], v[24:25]
	s_waitcnt lgkmcnt(1)
	v_pk_fma_f32 v[14:15], s[30:31], v[14:15], v[22:23] op_sel_hi:[0,1,1] neg_lo:[1,0,0] neg_hi:[1,0,0]
	s_waitcnt lgkmcnt(0)
	v_pk_fma_f32 v[20:21], s[30:31], v[38:39], v[20:21] op_sel_hi:[0,1,1] neg_lo:[1,0,0] neg_hi:[1,0,0]
	v_pk_mul_f32 v[22:23], v[14:15], v[14:15]
	v_pk_mul_f32 v[38:39], v[20:21], v[20:21]
	v_mov_b32_e32 v40, v32
	v_mov_b32_e32 v41, v36
	v_mov_b32_e32 v36, v33
	v_pk_add_f32 v[32:33], v[40:41], v[36:37]
	v_mov_b32_e32 v36, v38
	v_mov_b32_e32 v37, v22
	v_pk_add_f32 v[32:33], v[32:33], v[36:37]
	v_mov_b32_e32 v22, v39
	v_pk_add_f32 v[22:23], v[32:33], v[22:23]
	v_mul_f32_e32 v27, 0x4b800000, v26
	v_cmp_gt_f32_e32 vcc, s90, v26
	ds_write_b16 v94, v42 offset:4288
	s_waitcnt lgkmcnt(1)
	s_nop 1
	v_add_f32_dpp v22, v22, v22 quad_perm:[1,0,3,2] row_mask:0xf bank_mask:0xf
	v_add_f32_dpp v23, v23, v23 quad_perm:[1,0,3,2] row_mask:0xf bank_mask:0xf
	v_cndmask_b32_e32 v26, v26, v27, vcc
	v_rsq_f32_e32 v36, v26
	v_mul_f32_e32 v32, 0x45800000, v36
	v_cndmask_b32_e32 v32, v36, v32, vcc
	v_mul_f32_e32 v30, v30, v32
	s_waitcnt lgkmcnt(0)
	s_nop 1
	v_add_f32_dpp v22, v22, v22 quad_perm:[2,3,0,1] row_mask:0xf bank_mask:0xf
	v_add_f32_dpp v23, v23, v23 quad_perm:[2,3,0,1] row_mask:0xf bank_mask:0xf
	v_mul_f32_e32 v30, v105, v30
	v_cvt_pk_bf16_f32 v30, v30, s0
	ds_write_b16 v94, v30 offset:4352
	v_mul_f32_e32 v30, v31, v32
	s_waitcnt lgkmcnt(1)
	s_nop 1
	v_add_f32_dpp v22, v22, v22 row_half_mirror row_mask:0xf bank_mask:0xf
	v_add_f32_dpp v23, v23, v23 row_half_mirror row_mask:0xf bank_mask:0xf
	v_mul_f32_e32 v30, v104, v30
	v_cvt_pk_bf16_f32 v30, v30, s0
	ds_write_b16 v94, v30 offset:4416
	v_mul_f32_e32 v30, v34, v32
	s_waitcnt lgkmcnt(1)
	s_nop 1
	v_add_f32_dpp v22, v22, v22 row_ror:8 row_mask:0xf bank_mask:0xf
	v_add_f32_dpp v23, v23, v23 row_ror:8 row_mask:0xf bank_mask:0xf
	ds_bpermute_b32 v27, v215, v23
	ds_bpermute_b32 v26, v215, v22
	v_mul_f32_e32 v30, v95, v30
	v_cvt_pk_bf16_f32 v30, v30, s0
	ds_write_b16 v94, v30 offset:4480
	v_mul_f32_e32 v30, v35, v32
	s_waitcnt lgkmcnt(1)
	v_pk_add_f32 v[22:23], v[22:23], v[26:27]
	s_nop 0
	v_pk_fma_f32 v[22:23], v[22:23], s[0:1], v[8:9] op_sel_hi:[1,0,0]
	s_nop 0
	v_mul_f32_e32 v26, 0x4b800000, v23
	v_cmp_gt_f32_e32 vcc, s90, v23
	s_nop 1
	v_cndmask_b32_e32 v23, v23, v26, vcc
	v_rsq_f32_e32 v23, v23
	v_mul_f32_e32 v26, v93, v30
	v_cvt_pk_bf16_f32 v26, v26, s0
	ds_write_b16 v94, v26 offset:4544
	v_mul_f32_e32 v26, 0x45800000, v23
	v_cndmask_b32_e32 v23, v23, v26, vcc
	v_mul_f32_e32 v26, v28, v23
	v_mul_f32_e32 v26, v105, v26
	v_cvt_pk_bf16_f32 v26, v26, s0
	ds_write_b16 v94, v26 offset:4608
	v_mul_f32_e32 v26, v29, v23
	v_mul_f32_e32 v26, v104, v26
	v_cvt_pk_bf16_f32 v26, v26, s0
	ds_write_b16 v94, v26 offset:4672
	ds_read2_b32 v[26:27], v107 offset1:32
	v_mul_f32_e32 v14, v14, v23
	v_mul_f32_e32 v14, v95, v14
	v_cvt_pk_bf16_f32 v14, v14, s0
	ds_write_b16 v94, v14 offset:4736
	v_mul_f32_e32 v14, v15, v23
	v_mul_f32_e32 v14, v93, v14
	s_waitcnt lgkmcnt(1)
	v_pk_fma_f32 v[18:19], s[30:31], v[26:27], v[18:19] op_sel_hi:[0,1,1] neg_lo:[1,0,0] neg_hi:[1,0,0]
	ds_read2_b32 v[26:27], v107 offset0:128 offset1:160
	v_cvt_pk_bf16_f32 v34, v14, s0
	ds_read2_b32 v[14:15], v107 offset0:64 offset1:96
	ds_read2_b32 v[30:31], v107 offset0:192 offset1:224
	v_pk_mul_f32 v[28:29], v[18:19], v[18:19]
	s_waitcnt lgkmcnt(2)
	v_pk_fma_f32 v[12:13], s[30:31], v[26:27], v[12:13] op_sel_hi:[0,1,1] neg_lo:[1,0,0] neg_hi:[1,0,0]
	v_pk_mul_f32 v[26:27], v[12:13], v[12:13]
	s_waitcnt lgkmcnt(1)
	v_pk_fma_f32 v[10:11], s[30:31], v[14:15], v[10:11] op_sel_hi:[0,1,1] neg_lo:[1,0,0] neg_hi:[1,0,0]
	s_waitcnt lgkmcnt(0)
	v_pk_fma_f32 v[16:17], s[30:31], v[30:31], v[16:17] op_sel_hi:[0,1,1] neg_lo:[1,0,0] neg_hi:[1,0,0]
	v_pk_mul_f32 v[14:15], v[10:11], v[10:11]
	v_pk_mul_f32 v[30:31], v[16:17], v[16:17]
	v_mov_b32_e32 v32, v26
	v_mov_b32_e32 v33, v28
	v_mov_b32_e32 v28, v27
	v_pk_add_f32 v[26:27], v[32:33], v[28:29]
	v_mov_b32_e32 v28, v30
	v_mov_b32_e32 v29, v14
	v_pk_add_f32 v[26:27], v[26:27], v[28:29]
	v_mov_b32_e32 v14, v31
	v_pk_add_f32 v[14:15], v[26:27], v[14:15]
	v_mul_f32_e32 v23, 0x4b800000, v22
	v_cmp_gt_f32_e32 vcc, s90, v22
	ds_write_b16 v94, v34 offset:4800
	s_waitcnt lgkmcnt(1)
	s_nop 1
	v_add_f32_dpp v14, v14, v14 quad_perm:[1,0,3,2] row_mask:0xf bank_mask:0xf
	v_add_f32_dpp v15, v15, v15 quad_perm:[1,0,3,2] row_mask:0xf bank_mask:0xf
	v_cndmask_b32_e32 v22, v22, v23, vcc
	v_rsq_f32_e32 v28, v22
	v_mul_f32_e32 v26, 0x45800000, v28
	v_cndmask_b32_e32 v26, v28, v26, vcc
	v_mul_f32_e32 v20, v20, v26
	s_waitcnt lgkmcnt(0)
	s_nop 1
	v_add_f32_dpp v14, v14, v14 quad_perm:[2,3,0,1] row_mask:0xf bank_mask:0xf
	v_add_f32_dpp v15, v15, v15 quad_perm:[2,3,0,1] row_mask:0xf bank_mask:0xf
	v_mul_f32_e32 v20, v95, v20
	v_cvt_pk_bf16_f32 v20, v20, s0
	ds_write_b16 v94, v20 offset:4992
	v_mul_f32_e32 v20, v21, v26
	s_waitcnt lgkmcnt(1)
	s_nop 1
	v_add_f32_dpp v14, v14, v14 row_half_mirror row_mask:0xf bank_mask:0xf
	v_add_f32_dpp v15, v15, v15 row_half_mirror row_mask:0xf bank_mask:0xf
	v_mul_f32_e32 v20, v93, v20
	v_cvt_pk_bf16_f32 v20, v20, s0
	ds_write_b16 v94, v20 offset:5056
	v_mul_f32_e32 v24, v24, v26
	s_waitcnt lgkmcnt(1)
	s_nop 1
	v_add_f32_dpp v14, v14, v14 row_ror:8 row_mask:0xf bank_mask:0xf
	v_add_f32_dpp v15, v15, v15 row_ror:8 row_mask:0xf bank_mask:0xf
	ds_bpermute_b32 v23, v215, v15
	ds_bpermute_b32 v22, v215, v14
	v_mul_f32_e32 v24, v105, v24
	v_cvt_pk_bf16_f32 v24, v24, s0
	ds_write_b16 v94, v24 offset:4864
	v_mul_f32_e32 v24, v25, v26
	s_waitcnt lgkmcnt(1)
; #define LAS __attribute__((address_space(3)))
; DI bf16_t f2bf1(float f) { return (bf16_t)(pk2(f, 0.f) & 0xffffu); }
; DI int crow(int r, int hi) { return (r & 3) + 8 * (r >> 2) + 4 * hi; }
; template <bool SHIFT> DI void phase_attn2(const Params& p, const Grp& G, int layer, LAS unsigned char* lds, int tid, int wave, int lane, int vcu, bool dry) {
;     ...
;                 for (int r = 0; r < 16; ++r) {
;                     float a[4]; float ss = 0.f;
; #pragma unroll
;                     for (int cb = 0; cb < 4; ++cb) { a[cb] = o[rbq][cb][r] - lamv * ex[crow(r, hiv) * 128 + 32 * cb + l31v]; ss += a[cb] * a[cb]; }
;                     ss = half_sum32(ss); const float ri = rsqrtf(ss * (1.0f / 128.0f) + EPSN);
;                     LAS bf16_t* sp = (LAS bf16_t*)(stg + crow(r, hiv) * 256) + l31v;
; #pragma unroll
;                     for (int cb = 0; cb < 4; ++cb) sp[32 * cb] = f2bf1(a[cb] * ri * sw[cb]);
;                 }
	v_pk_add_f32 v[14:15], v[14:15], v[22:23]
	ds_read2_b32 v[22:23], v106 offset0:192 offset1:224
	v_pk_fma_f32 v[14:15], v[14:15], s[0:1], v[8:9] op_sel_hi:[1,0,0]
	v_mul_f32_e32 v24, v104, v24
	v_mul_f32_e32 v21, 0x4b800000, v15
	v_cmp_gt_f32_e32 vcc, s90, v15
	v_cvt_pk_bf16_f32 v24, v24, s0
	s_waitcnt lgkmcnt(0)
	v_pk_fma_f32 v[4:5], s[30:31], v[22:23], v[4:5] op_sel_hi:[0,1,1] neg_lo:[1,0,0] neg_hi:[1,0,0]
	v_cndmask_b32_e32 v15, v15, v21, vcc
	v_rsq_f32_e32 v15, v15
	ds_write_b16 v94, v24 offset:4928
	v_pk_mul_f32 v[22:23], v[4:5], v[4:5]
	v_mul_f32_e32 v20, 0x45800000, v15
	v_cndmask_b32_e32 v15, v15, v20, vcc
	v_mul_f32_e32 v18, v18, v15
	v_mul_f32_e32 v18, v105, v18
	v_cvt_pk_bf16_f32 v18, v18, s0
	ds_write_b16 v94, v18 offset:6144
	v_mul_f32_e32 v18, v19, v15
	v_mul_f32_e32 v18, v104, v18
	v_cvt_pk_bf16_f32 v18, v18, s0
	ds_write_b16 v94, v18 offset:6208
	ds_read2_b32 v[18:19], v106 offset1:32
	v_mul_f32_e32 v10, v10, v15
	v_mul_f32_e32 v10, v95, v10
	v_cvt_pk_bf16_f32 v10, v10, s0
	ds_write_b16 v94, v10 offset:6272
	v_mul_f32_e32 v10, v11, v15
	v_mul_f32_e32 v10, v93, v10
	s_waitcnt lgkmcnt(1)
	v_pk_fma_f32 v[6:7], s[30:31], v[18:19], v[6:7] op_sel_hi:[0,1,1] neg_lo:[1,0,0] neg_hi:[1,0,0]
	ds_read2_b32 v[18:19], v106 offset0:128 offset1:160
	v_cvt_pk_bf16_f32 v26, v10, s0
	ds_read2_b32 v[10:11], v106 offset0:64 offset1:96
	v_pk_mul_f32 v[20:21], v[6:7], v[6:7]
	v_mul_f32_e32 v15, 0x4b800000, v14
	s_waitcnt lgkmcnt(1)
	v_pk_fma_f32 v[2:3], s[30:31], v[18:19], v[2:3] op_sel_hi:[0,1,1] neg_lo:[1,0,0] neg_hi:[1,0,0]
	v_pk_mul_f32 v[18:19], v[2:3], v[2:3]
	s_waitcnt lgkmcnt(0)
	v_pk_fma_f32 v[0:1], s[30:31], v[10:11], v[0:1] op_sel_hi:[0,1,1] neg_lo:[1,0,0] neg_hi:[1,0,0]
	v_pk_mul_f32 v[10:11], v[0:1], v[0:1]
	v_mov_b32_e32 v24, v18
	v_mov_b32_e32 v25, v20
	v_mov_b32_e32 v20, v19
	v_pk_add_f32 v[18:19], v[24:25], v[20:21]
	v_mov_b32_e32 v20, v22
	v_mov_b32_e32 v21, v10
	v_pk_add_f32 v[18:19], v[18:19], v[20:21]
	v_mov_b32_e32 v10, v23
	v_pk_add_f32 v[10:11], v[18:19], v[10:11]
	v_cmp_gt_f32_e32 vcc, s90, v14
	ds_write_b16 v94, v26 offset:6336
	s_waitcnt lgkmcnt(1)
	s_nop 1
	v_add_f32_dpp v10, v10, v10 quad_perm:[1,0,3,2] row_mask:0xf bank_mask:0xf
	v_add_f32_dpp v11, v11, v11 quad_perm:[1,0,3,2] row_mask:0xf bank_mask:0xf
	v_cndmask_b32_e32 v14, v14, v15, vcc
	v_rsq_f32_e32 v20, v14
	v_mul_f32_e32 v18, 0x45800000, v20
	v_cndmask_b32_e32 v18, v20, v18, vcc
	v_mul_f32_e32 v12, v12, v18
	s_waitcnt lgkmcnt(0)
	s_nop 1
	v_add_f32_dpp v10, v10, v10 quad_perm:[2,3,0,1] row_mask:0xf bank_mask:0xf
	v_add_f32_dpp v11, v11, v11 quad_perm:[2,3,0,1] row_mask:0xf bank_mask:0xf
	v_mul_f32_e32 v12, v105, v12
	v_cvt_pk_bf16_f32 v12, v12, s0
	ds_write_b16 v94, v12 offset:6400
	v_mul_f32_e32 v19, v13, v18
	s_waitcnt lgkmcnt(1)
	s_nop 1
	v_add_f32_dpp v10, v10, v10 row_half_mirror row_mask:0xf bank_mask:0xf
	v_add_f32_dpp v11, v11, v11 row_half_mirror row_mask:0xf bank_mask:0xf
	v_mul_f32_e32 v14, v104, v19
	v_cvt_pk_bf16_f32 v14, v14, s0
	ds_write_b16 v94, v14 offset:6464
	v_mul_f32_e32 v14, v16, v18
	s_waitcnt lgkmcnt(1)
	s_nop 1
	v_add_f32_dpp v10, v10, v10 row_ror:8 row_mask:0xf bank_mask:0xf
	v_add_f32_dpp v11, v11, v11 row_ror:8 row_mask:0xf bank_mask:0xf
	ds_bpermute_b32 v13, v215, v11
	ds_bpermute_b32 v12, v215, v10
	v_mul_f32_e32 v14, v95, v14
	v_cvt_pk_bf16_f32 v14, v14, s0
	ds_write_b16 v94, v14 offset:6528
	v_mul_f32_e32 v14, v17, v18
	s_waitcnt lgkmcnt(1)
; #define LAS __attribute__((address_space(3)))
; DI bf16_t f2bf1(float f) { return (bf16_t)(pk2(f, 0.f) & 0xffffu); }
; DI int crow(int r, int hi) { return (r & 3) + 8 * (r >> 2) + 4 * hi; }
; template <bool SHIFT> DI void phase_attn2(const Params& p, const Grp& G, int layer, LAS unsigned char* lds, int tid, int wave, int lane, int vcu, bool dry) {
;     ...
;                     for (int cb = 0; cb < 4; ++cb) { a[cb] = o[rbq][cb][r] - lamv * ex[crow(r, hiv) * 128 + 32 * cb + l31v]; ss += a[cb] * a[cb]; }
;                     ss = half_sum32(ss); const float ri = rsqrtf(ss * (1.0f / 128.0f) + EPSN);
;                     LAS bf16_t* sp = (LAS bf16_t*)(stg + crow(r, hiv) * 256) + l31v;
; #pragma unroll
;                     for (int cb = 0; cb < 4; ++cb) sp[32 * cb] = f2bf1(a[cb] * ri * sw[cb]);
;                 }
;                 asm volatile("s_waitcnt lgkmcnt(0)" ::: "memory");
; #pragma unroll
;                 for (int i = 0; i < 8; ++i) { const int q = lanev + 64 * i, row = q >> 4, ch = q & 15;
;                     const u32x4 v = *(const LAS u32x4*)(stg + row * 256 + ch * 16);
;                     *(u32x4*)(obase + (size_t)(64 * qg + 32 * rbq + row) * MIXW + h * 128 + ch * 8) = v; }
;                 asm volatile("s_waitcnt lgkmcnt(0)" ::: "memory");
	v_pk_add_f32 v[10:11], v[10:11], v[12:13]
	s_nop 0
	v_pk_fma_f32 v[8:9], v[10:11], s[0:1], v[8:9] op_sel_hi:[1,0,0]
	s_nop 0
	v_mul_f32_e32 v10, 0x4b800000, v9
	v_cmp_gt_f32_e32 vcc, s90, v9
	s_nop 1
	v_cndmask_b32_e32 v9, v9, v10, vcc
	v_rsq_f32_e32 v9, v9
	v_mul_f32_e32 v10, v93, v14
	v_cvt_pk_bf16_f32 v10, v10, s0
	ds_write_b16 v94, v10 offset:6592
	v_mul_f32_e32 v10, 0x45800000, v9
	v_cndmask_b32_e32 v9, v9, v10, vcc
	v_mul_f32_e32 v0, v0, v9
	v_mul_f32_e32 v0, v95, v0
	v_cvt_pk_bf16_f32 v0, v0, s0
	ds_write_b16 v94, v0 offset:6784
	v_mul_f32_e32 v0, v1, v9
	v_mul_f32_e32 v1, 0x4b800000, v8
	v_cmp_gt_f32_e32 vcc, s90, v8
	v_mul_f32_e32 v0, v93, v0
	v_cvt_pk_bf16_f32 v0, v0, s0
	v_cndmask_b32_e32 v1, v8, v1, vcc
	v_rsq_f32_e32 v1, v1
	ds_write_b16 v94, v0 offset:6848
	v_mul_f32_e32 v6, v6, v9
	v_mul_f32_e32 v6, v105, v6
	v_mul_f32_e32 v0, 0x45800000, v1
	v_cndmask_b32_e32 v0, v1, v0, vcc
	v_mul_f32_e32 v1, v2, v0
	v_mul_f32_e32 v1, v105, v1
	v_cvt_pk_bf16_f32 v1, v1, s0
	ds_write_b16 v94, v1 offset:6912
	v_mul_f32_e32 v1, v3, v0
	v_mul_f32_e32 v1, v104, v1
	v_cvt_pk_bf16_f32 v6, v6, s0
	v_cvt_pk_bf16_f32 v1, v1, s0
	ds_write_b16 v94, v6 offset:6656
	v_mul_f32_e32 v6, v7, v9
	ds_write_b16 v94, v1 offset:6976
	v_mul_f32_e32 v1, v4, v0
	v_mul_f32_e32 v0, v5, v0
	v_mul_f32_e32 v6, v104, v6
	v_mul_f32_e32 v1, v95, v1
	v_mul_f32_e32 v0, v93, v0
	v_cvt_pk_bf16_f32 v6, v6, s0
	v_cvt_pk_bf16_f32 v1, v1, s0
	v_cvt_pk_bf16_f32 v0, v0, s0
	v_ashrrev_i32_e32 v4, 4, v128
	v_readlane_b32 s0, v253, 15
	ds_write_b16 v94, v6 offset:6720
	ds_write_b16 v94, v1 offset:7040
	ds_write_b16 v94, v0 offset:7104
	v_lshl_add_u32 v0, v4, 8, v92
	v_add_u32_e32 v4, s0, v4
	s_waitcnt lgkmcnt(0)
	v_ashrrev_i32_e32 v5, 31, v4
	ds_read_b128 v[0:3], v0
	v_lshlrev_b64 v[4:5], 11, v[4:5]
	v_lshl_add_u64 v[8:9], v[64:65], 0, v[4:5]
	v_add_u32_e32 v4, 64, v128
	v_ashrrev_i32_e32 v10, 4, v4
	v_lshl_add_u32 v4, v10, 8, v92
	ds_read_b128 v[4:7], v4
	s_waitcnt lgkmcnt(1)
	global_store_dwordx4 v[8:9], v[0:3], off
	s_nop 1
	v_add_u32_e32 v0, s0, v10
	v_ashrrev_i32_e32 v1, 31, v0
	v_lshlrev_b64 v[0:1], 11, v[0:1]
	v_lshl_add_u64 v[0:1], v[64:65], 0, v[0:1]
	s_waitcnt lgkmcnt(0)
	global_store_dwordx4 v[0:1], v[4:7], off
	v_add_u32_e32 v0, 0x80, v128
	s_nop 0
	v_ashrrev_i32_e32 v4, 4, v0
	v_lshl_add_u32 v0, v4, 8, v92
	v_add_u32_e32 v4, s0, v4
	v_ashrrev_i32_e32 v5, 31, v4
	ds_read_b128 v[0:3], v0
	v_lshlrev_b64 v[4:5], 11, v[4:5]
	v_lshl_add_u64 v[8:9], v[64:65], 0, v[4:5]
	v_add_u32_e32 v4, 0xc0, v128
	v_ashrrev_i32_e32 v10, 4, v4
	v_lshl_add_u32 v4, v10, 8, v92
	ds_read_b128 v[4:7], v4
	s_waitcnt lgkmcnt(1)
	global_store_dwordx4 v[8:9], v[0:3], off
	s_nop 1
	v_add_u32_e32 v0, s0, v10
	v_ashrrev_i32_e32 v1, 31, v0
	v_lshlrev_b64 v[0:1], 11, v[0:1]
	v_lshl_add_u64 v[0:1], v[64:65], 0, v[0:1]
	s_waitcnt lgkmcnt(0)
	global_store_dwordx4 v[0:1], v[4:7], off
	v_add_u32_e32 v0, 0x100, v128
	s_nop 0
	v_ashrrev_i32_e32 v4, 4, v0
	v_lshl_add_u32 v0, v4, 8, v92
	v_add_u32_e32 v4, s0, v4
	v_ashrrev_i32_e32 v5, 31, v4
	ds_read_b128 v[0:3], v0
	v_lshlrev_b64 v[4:5], 11, v[4:5]
	v_lshl_add_u64 v[8:9], v[64:65], 0, v[4:5]
	v_add_u32_e32 v4, 0x140, v128
	v_ashrrev_i32_e32 v10, 4, v4
	v_lshl_add_u32 v4, v10, 8, v92
	ds_read_b128 v[4:7], v4
	s_waitcnt lgkmcnt(1)
	global_store_dwordx4 v[8:9], v[0:3], off
	s_nop 1
	v_add_u32_e32 v0, s0, v10
	v_ashrrev_i32_e32 v1, 31, v0
	v_lshlrev_b64 v[0:1], 11, v[0:1]
	v_lshl_add_u64 v[0:1], v[64:65], 0, v[0:1]
	s_waitcnt lgkmcnt(0)
	global_store_dwordx4 v[0:1], v[4:7], off
	v_add_u32_e32 v0, 0x180, v128
	s_nop 0
	v_ashrrev_i32_e32 v4, 4, v0
	v_lshl_add_u32 v0, v4, 8, v92
	v_add_u32_e32 v4, s0, v4
	v_ashrrev_i32_e32 v5, 31, v4
	ds_read_b128 v[0:3], v0
	v_lshlrev_b64 v[4:5], 11, v[4:5]
	v_lshl_add_u64 v[8:9], v[64:65], 0, v[4:5]
	v_add_u32_e32 v4, 0x1c0, v128
	v_ashrrev_i32_e32 v10, 4, v4
	v_lshl_add_u32 v4, v10, 8, v92
	ds_read_b128 v[4:7], v4
	s_waitcnt lgkmcnt(1)
	global_store_dwordx4 v[8:9], v[0:3], off
	s_nop 1
	v_add_u32_e32 v0, s0, v10
	v_ashrrev_i32_e32 v1, 31, v0
	v_lshlrev_b64 v[0:1], 11, v[0:1]
	v_lshl_add_u64 v[0:1], v[64:65], 0, v[0:1]
	s_waitcnt lgkmcnt(0)
	global_store_dwordx4 v[0:1], v[4:7], off
	s_waitcnt lgkmcnt(0)
	s_branch .LBB0_376

; #define LAS __attribute__((address_space(3)))
; #define MFMA32(a, b, c) __builtin_amdgcn_mfma_f32_32x32x16_bf16((a), (b), (c), 0, 0, 0)
; DI void phase_ret_out(const Params& p, const Grp& G, int layer, LAS unsigned char* lds, int tid, int wave, int lane, bool dry) {
;     ...
;         for (int dir = 0; dir < 2; ++dir) {
;             const LAS bf16_t* S = Sl + (hh * 2 + dir) * 4096; f32x16 t[2]; t[0] = f32x16{}; t[1] = f32x16{};
; #pragma unroll
;             for (int ks = 0; ks < 4; ++ks) {
; #pragma unroll
;                 for (int cb = 0; cb < 2; ++cb) { const LAS bf16_t* sp = S + (16 * ks + 8 * hi) * 64 + 32 * cb + l31;
;                     u32x4 w; w.x = (unsigned)sp[0] | ((unsigned)sp[64] << 16); w.y = (unsigned)sp[128] | ((unsigned)sp[192] << 16); w.z = (unsigned)sp[256] | ((unsigned)sp[320] << 16); w.w = (unsigned)sp[384] | ((unsigned)sp[448] << 16);
;                     t[cb] = MFMA32(qf[ks], __builtin_bit_cast(bf16x8, w), t[cb]); }
;                 asm volatile("" ::: "memory"); }
.LBB0_424:
	v_cndmask_b32_e64 v16, 0, 1, s[30:31]
	v_add_u32_e32 v227, s0, v151
	v_cmp_ne_u32_e32 vcc, 1, v16
	ds_read_u16 v16, v227
	ds_read_u16 v17, v227 offset:128
	s_movk_i32 s0, 0x2000
	s_and_b64 vcc, exec, vcc
	s_waitcnt lgkmcnt(0)
	v_lshl_or_b32 v16, v17, 16, v16
	ds_read_u16 v17, v227 offset:256
	ds_read_u16 v18, v227 offset:384
	s_waitcnt lgkmcnt(0)
	v_lshl_or_b32 v17, v18, 16, v17
	ds_read_u16 v18, v227 offset:512
	ds_read_u16 v19, v227 offset:640
	s_waitcnt lgkmcnt(0)
	v_lshl_or_b32 v18, v19, 16, v18
	ds_read_u16 v19, v227 offset:768
	ds_read_u16 v20, v227 offset:896
	ds_read_u16 v32, v227 offset:64
	ds_read_u16 v33, v227 offset:192
	s_waitcnt lgkmcnt(2)
	v_lshl_or_b32 v19, v20, 16, v19
	s_waitcnt lgkmcnt(0)
	v_lshl_or_b32 v32, v33, 16, v32
	ds_read_u16 v33, v227 offset:320
	ds_read_u16 v34, v227 offset:448
	v_mfma_f32_32x32x16_bf16 v[16:31], v[112:115], v[16:19], 0
	s_waitcnt lgkmcnt(0)
	v_lshl_or_b32 v33, v34, 16, v33
	ds_read_u16 v34, v227 offset:576
	ds_read_u16 v35, v227 offset:704
	s_waitcnt lgkmcnt(0)
	v_lshl_or_b32 v34, v35, 16, v34
	ds_read_u16 v35, v227 offset:832
	ds_read_u16 v36, v227 offset:960
	ds_read_u16 v228, v227 offset:2048
	ds_read_u16 v229, v227 offset:2176
	s_waitcnt lgkmcnt(2)
	v_lshl_or_b32 v35, v36, 16, v35
	s_nop 1
	v_mfma_f32_32x32x16_bf16 v[32:47], v[112:115], v[32:35], 0
	s_waitcnt lgkmcnt(0)
	v_lshl_or_b32 v228, v229, 16, v228
	ds_read_u16 v229, v227 offset:2304
	ds_read_u16 v230, v227 offset:2432
	s_waitcnt lgkmcnt(0)
	v_lshl_or_b32 v229, v230, 16, v229
	ds_read_u16 v230, v227 offset:2560
	ds_read_u16 v231, v227 offset:2688
	s_waitcnt lgkmcnt(0)
	v_lshl_or_b32 v230, v231, 16, v230
	ds_read_u16 v231, v227 offset:2816
	ds_read_u16 v232, v227 offset:2944
	s_waitcnt lgkmcnt(0)
	v_lshl_or_b32 v231, v232, 16, v231
	s_nop 1
	v_mfma_f32_32x32x16_bf16 v[16:31], v[116:119], v[228:231], v[16:31]
	ds_read_u16 v228, v227 offset:2112
	ds_read_u16 v229, v227 offset:2240
	s_waitcnt lgkmcnt(0)
	v_lshl_or_b32 v228, v229, 16, v228
	ds_read_u16 v229, v227 offset:2368
	ds_read_u16 v230, v227 offset:2496
	s_waitcnt lgkmcnt(0)
	v_lshl_or_b32 v229, v230, 16, v229
	ds_read_u16 v230, v227 offset:2624
	ds_read_u16 v231, v227 offset:2752
	s_waitcnt lgkmcnt(0)
	v_lshl_or_b32 v230, v231, 16, v230
	ds_read_u16 v231, v227 offset:2880
	ds_read_u16 v232, v227 offset:3008
	s_waitcnt lgkmcnt(0)
	v_lshl_or_b32 v231, v232, 16, v231
	s_nop 1
	v_mfma_f32_32x32x16_bf16 v[32:47], v[116:119], v[228:231], v[32:47]
	ds_read_u16 v228, v227 offset:4096
	ds_read_u16 v229, v227 offset:4224
	s_waitcnt lgkmcnt(0)
	v_lshl_or_b32 v228, v229, 16, v228
	ds_read_u16 v229, v227 offset:4352
	ds_read_u16 v230, v227 offset:4480
	s_waitcnt lgkmcnt(0)
	v_lshl_or_b32 v229, v230, 16, v229
	ds_read_u16 v230, v227 offset:4608
	ds_read_u16 v231, v227 offset:4736
	s_waitcnt lgkmcnt(0)
	v_lshl_or_b32 v230, v231, 16, v230
	ds_read_u16 v231, v227 offset:4864
	ds_read_u16 v232, v227 offset:4992
	s_waitcnt lgkmcnt(0)
	v_lshl_or_b32 v231, v232, 16, v231
	s_nop 1
	v_mfma_f32_32x32x16_bf16 v[16:31], v[120:123], v[228:231], v[16:31]
	ds_read_u16 v228, v227 offset:4160
	ds_read_u16 v229, v227 offset:4288
	s_waitcnt lgkmcnt(0)
	v_lshl_or_b32 v228, v229, 16, v228
	ds_read_u16 v229, v227 offset:4416
	ds_read_u16 v230, v227 offset:4544
	s_waitcnt lgkmcnt(0)
	v_lshl_or_b32 v229, v230, 16, v229
	ds_read_u16 v230, v227 offset:4672
	ds_read_u16 v231, v227 offset:4800
	s_waitcnt lgkmcnt(0)
	v_lshl_or_b32 v230, v231, 16, v230
	ds_read_u16 v231, v227 offset:4928
	ds_read_u16 v232, v227 offset:5056
	s_waitcnt lgkmcnt(0)
	v_lshl_or_b32 v231, v232, 16, v231
	s_nop 1
	v_mfma_f32_32x32x16_bf16 v[32:47], v[120:123], v[228:231], v[32:47]
	ds_read_u16 v228, v227 offset:6144
	ds_read_u16 v229, v227 offset:6272
	s_waitcnt lgkmcnt(0)
	v_lshl_or_b32 v228, v229, 16, v228
	ds_read_u16 v229, v227 offset:6400
	ds_read_u16 v230, v227 offset:6528
	s_waitcnt lgkmcnt(0)
	v_lshl_or_b32 v229, v230, 16, v229
	ds_read_u16 v230, v227 offset:6656
	ds_read_u16 v231, v227 offset:6784
	s_waitcnt lgkmcnt(0)
	v_lshl_or_b32 v230, v231, 16, v230
	ds_read_u16 v231, v227 offset:6912
	ds_read_u16 v232, v227 offset:7040
	s_waitcnt lgkmcnt(0)
	v_lshl_or_b32 v231, v232, 16, v231
	s_nop 1
	v_mfma_f32_32x32x16_bf16 v[16:31], v[124:127], v[228:231], v[16:31]
	ds_read_u16 v228, v227 offset:6208
	ds_read_u16 v229, v227 offset:6336
	s_waitcnt lgkmcnt(0)
	v_lshl_or_b32 v228, v229, 16, v228
	ds_read_u16 v229, v227 offset:6464
	ds_read_u16 v230, v227 offset:6592
	s_waitcnt lgkmcnt(0)
	v_lshl_or_b32 v229, v230, 16, v229
	ds_read_u16 v230, v227 offset:6720
	ds_read_u16 v231, v227 offset:6848
	s_waitcnt lgkmcnt(0)
	v_lshl_or_b32 v230, v231, 16, v230
	ds_read_u16 v231, v227 offset:6976
	ds_read_u16 v227, v227 offset:7104
	s_waitcnt lgkmcnt(0)
; #define LAS __attribute__((address_space(3)))
; DI int crow(int r, int hi) { return (r & 3) + 8 * (r >> 2) + 4 * hi; }
; DI void phase_ret_out(const Params& p, const Grp& G, int layer, LAS unsigned char* lds, int tid, int wave, int lane, bool dry) {
;     ...
; #pragma unroll
;             for (int r = 0; r < 16; ++r) { const int nrow = 32 * qg + crow(r, hi); const float sc = dir == 0 ? __builtin_amdgcn_exp2f(lgf * (float)(nrow + 1)) : __builtin_amdgcn_exp2f(lgb * (float)(128 - nrow));
;                 o[0][r] += t[0][r] * sc; o[1][r] += t[1][r] * sc; }
;         }
;         const float g0 = p.gn[layer * 64 + l31], g1 = p.gn[layer * 64 + 32 + l31];
;         __syncthreads();
;         LAS float* stg = (LAS float*)(lds + wave * 8192);
; #pragma unroll
;         for (int r = 0; r < 16; ++r) {
;             float ss = o[0][r] * o[0][r] + o[1][r] * o[1][r]; ss = half_sum32(ss); const float ri = rsqrtf(ss * (1.0f / 64.0f) + EPSN);
;             LAS float* sp = stg + crow(r, hi) * 64 + l31; sp[0] = o[0][r] * ri * g0; sp[32] = o[1][r] * ri * g1;
;         }
	v_lshl_or_b32 v231, v227, 16, v231
	s_nop 1
	v_mfma_f32_32x32x16_bf16 v[32:47], v[124:127], v[228:231], v[32:47]
	v_mov_b32_e32 v230, v16
	v_cndmask_b32_e64 v16, v190, v191, s[30:31]
	v_cndmask_b32_e64 v228, v188, v189, s[30:31]
	s_nop 8
	v_mov_b32_e32 v231, v32
	v_mov_b32_e32 v32, v17
	v_pk_fma_f32 v[148:149], v[16:17], v[32:33], v[148:149] op_sel_hi:[0,1,1]
	v_cndmask_b32_e64 v16, v192, v196, s[30:31]
	v_mov_b32_e32 v32, v18
	v_mov_b32_e32 v33, v34
	v_pk_fma_f32 v[2:3], v[16:17], v[32:33], v[2:3] op_sel_hi:[0,1,1]
	v_cndmask_b32_e64 v16, v197, v198, s[30:31]
	v_mov_b32_e32 v34, v19
	v_pk_fma_f32 v[146:147], v[16:17], v[34:35], v[146:147] op_sel_hi:[0,1,1]
	v_cndmask_b32_e64 v16, v199, v200, s[30:31]
	v_mov_b32_e32 v18, v20
	v_mov_b32_e32 v19, v36
	v_pk_fma_f32 v[4:5], v[16:17], v[18:19], v[4:5] op_sel_hi:[0,1,1]
	v_cndmask_b32_e64 v16, v201, v202, s[30:31]
	v_mov_b32_e32 v36, v21
	v_pk_fma_f32 v[144:145], v[16:17], v[36:37], v[144:145] op_sel_hi:[0,1,1]
	v_cndmask_b32_e64 v16, v203, v204, s[30:31]
	v_mov_b32_e32 v18, v22
	v_mov_b32_e32 v19, v38
	v_pk_fma_f32 v[6:7], v[16:17], v[18:19], v[6:7] op_sel_hi:[0,1,1]
	v_cndmask_b32_e64 v16, v205, v206, s[30:31]
	v_mov_b32_e32 v38, v23
	v_pk_fma_f32 v[142:143], v[16:17], v[38:39], v[142:143] op_sel_hi:[0,1,1]
	v_cndmask_b32_e64 v16, v207, v208, s[30:31]
	v_mov_b32_e32 v18, v24
	v_mov_b32_e32 v19, v40
	v_pk_fma_f32 v[8:9], v[16:17], v[18:19], v[8:9] op_sel_hi:[0,1,1]
	v_cndmask_b32_e64 v16, v209, v210, s[30:31]
	v_mov_b32_e32 v40, v25
	v_pk_fma_f32 v[140:141], v[16:17], v[40:41], v[140:141] op_sel_hi:[0,1,1]
	v_cndmask_b32_e64 v16, v211, v216, s[30:31]
	v_mov_b32_e32 v18, v26
	v_mov_b32_e32 v19, v42
	v_pk_fma_f32 v[10:11], v[16:17], v[18:19], v[10:11] op_sel_hi:[0,1,1]
	v_cndmask_b32_e64 v16, v217, v218, s[30:31]
	v_mov_b32_e32 v42, v27
	v_pk_fma_f32 v[138:139], v[16:17], v[42:43], v[138:139] op_sel_hi:[0,1,1]
	v_cndmask_b32_e64 v16, v219, v220, s[30:31]
	v_mov_b32_e32 v18, v28
	v_mov_b32_e32 v19, v44
	v_pk_fma_f32 v[12:13], v[16:17], v[18:19], v[12:13] op_sel_hi:[0,1,1]
	v_cndmask_b32_e64 v16, v221, v222, s[30:31]
	v_mov_b32_e32 v44, v29
	v_pk_fma_f32 v[136:137], v[16:17], v[44:45], v[136:137] op_sel_hi:[0,1,1]
	v_cndmask_b32_e64 v16, v223, v224, s[30:31]
	v_mov_b32_e32 v18, v30
	v_mov_b32_e32 v19, v46
	v_pk_fma_f32 v[14:15], v[16:17], v[18:19], v[14:15] op_sel_hi:[0,1,1]
	v_cndmask_b32_e64 v16, v225, v226, s[30:31]
	v_mov_b32_e32 v46, v31
	v_pk_fma_f32 v[0:1], v[228:229], v[230:231], v[0:1] op_sel_hi:[0,1,1]
	v_pk_fma_f32 v[134:135], v[16:17], v[46:47], v[134:135] op_sel_hi:[0,1,1]
	s_mov_b64 s[30:31], 0
	s_cbranch_vccz .LBB0_424
	global_load_dword v19, v[132:133], off
	global_load_dword v18, v[132:133], off offset:128
	v_pk_mul_f32 v[16:17], v[0:1], v[0:1]
	v_pk_mul_f32 v[20:21], v[148:149], v[148:149]
	v_mov_b32_e32 v23, v16
	v_mov_b32_e32 v22, v20
	v_mov_b32_e32 v16, v21
	v_pk_add_f32 v[16:17], v[22:23], v[16:17]
	s_mov_b32 s0, 0x358637bd
	s_waitcnt lgkmcnt(0)
	s_barrier
	s_nop 1
	v_add_f32_dpp v16, v16, v16 quad_perm:[1,0,3,2] row_mask:0xf bank_mask:0xf
	v_add_f32_dpp v17, v17, v17 quad_perm:[1,0,3,2] row_mask:0xf bank_mask:0xf
	s_waitcnt lgkmcnt(0)
	s_nop 1
	v_add_f32_dpp v16, v16, v16 quad_perm:[2,3,0,1] row_mask:0xf bank_mask:0xf
	v_add_f32_dpp v17, v17, v17 quad_perm:[2,3,0,1] row_mask:0xf bank_mask:0xf
	s_waitcnt lgkmcnt(0)
	s_nop 1
	v_add_f32_dpp v16, v16, v16 row_half_mirror row_mask:0xf bank_mask:0xf
	v_add_f32_dpp v17, v17, v17 row_half_mirror row_mask:0xf bank_mask:0xf
	s_waitcnt lgkmcnt(0)
	s_nop 1
	v_add_f32_dpp v16, v16, v16 row_ror:8 row_mask:0xf bank_mask:0xf
	v_add_f32_dpp v17, v17, v17 row_ror:8 row_mask:0xf bank_mask:0xf
	ds_bpermute_b32 v21, v215, v17
	ds_bpermute_b32 v20, v215, v16
	s_waitcnt lgkmcnt(0)
	v_pk_add_f32 v[20:21], v[16:17], v[20:21]
	v_mov_b64_e32 v[16:17], s[0:1]
	s_mov_b32 s0, 0x3c800000
	v_pk_fma_f32 v[20:21], v[20:21], s[0:1], v[16:17] op_sel_hi:[1,0,0]
	s_nop 0
	v_mul_f32_e32 v22, 0x4b800000, v21
	v_cmp_gt_f32_e64 s[38:39], s90, v21
	v_cmp_gt_f32_e32 vcc, s90, v20
	s_nop 0
	v_cndmask_b32_e64 v21, v21, v22, s[38:39]
	v_rsq_f32_e32 v21, v21
	s_nop 0
	v_mul_f32_e32 v22, 0x45800000, v21
	v_cndmask_b32_e64 v21, v21, v22, s[38:39]
	v_mul_f32_e32 v0, v0, v21
	v_mul_f32_e32 v1, v1, v21
	s_waitcnt vmcnt(1)
	v_mul_f32_e32 v0, v19, v0
	s_waitcnt vmcnt(0)
	v_mul_f32_e32 v1, v18, v1
	ds_write2_b32 v152, v0, v1 offset1:32
	v_mul_f32_e32 v0, 0x4b800000, v20
	v_cndmask_b32_e32 v0, v20, v0, vcc
	v_rsq_f32_e32 v0, v0
	v_pk_mul_f32 v[20:21], v[146:147], v[146:147]
	v_mul_f32_e32 v1, 0x45800000, v0
	v_cndmask_b32_e32 v0, v0, v1, vcc
	v_mul_f32_e32 v1, v148, v0
	v_mul_f32_e32 v0, v149, v0
	v_mul_f32_e32 v1, v19, v1
	v_mul_f32_e32 v0, v18, v0
	ds_write2_b32 v152, v1, v0 offset0:64 offset1:96
	v_pk_mul_f32 v[0:1], v[2:3], v[2:3]
	v_mov_b32_e32 v22, v20
	v_mov_b32_e32 v23, v0
	v_mov_b32_e32 v0, v21
	v_pk_add_f32 v[0:1], v[22:23], v[0:1]
	s_waitcnt lgkmcnt(0)
	s_nop 1
	v_add_f32_dpp v0, v0, v0 quad_perm:[1,0,3,2] row_mask:0xf bank_mask:0xf
	v_add_f32_dpp v1, v1, v1 quad_perm:[1,0,3,2] row_mask:0xf bank_mask:0xf
	s_waitcnt lgkmcnt(0)
	s_nop 1
	v_add_f32_dpp v0, v0, v0 quad_perm:[2,3,0,1] row_mask:0xf bank_mask:0xf
	v_add_f32_dpp v1, v1, v1 quad_perm:[2,3,0,1] row_mask:0xf bank_mask:0xf
	s_waitcnt lgkmcnt(0)
	s_nop 1
	v_add_f32_dpp v0, v0, v0 row_half_mirror row_mask:0xf bank_mask:0xf
	v_add_f32_dpp v1, v1, v1 row_half_mirror row_mask:0xf bank_mask:0xf
	s_waitcnt lgkmcnt(0)
	s_nop 1
	v_add_f32_dpp v0, v0, v0 row_ror:8 row_mask:0xf bank_mask:0xf
	v_add_f32_dpp v1, v1, v1 row_ror:8 row_mask:0xf bank_mask:0xf
	ds_bpermute_b32 v21, v215, v1
	ds_bpermute_b32 v20, v215, v0
	s_waitcnt lgkmcnt(0)
; #define LAS __attribute__((address_space(3)))
; DI int crow(int r, int hi) { return (r & 3) + 8 * (r >> 2) + 4 * hi; }
; DI void phase_ret_out(const Params& p, const Grp& G, int layer, LAS unsigned char* lds, int tid, int wave, int lane, bool dry) {
;     ...
; #pragma unroll
;         for (int r = 0; r < 16; ++r) {
;             float ss = o[0][r] * o[0][r] + o[1][r] * o[1][r]; ss = half_sum32(ss); const float ri = rsqrtf(ss * (1.0f / 64.0f) + EPSN);
;             LAS float* sp = stg + crow(r, hi) * 64 + l31; sp[0] = o[0][r] * ri * g0; sp[32] = o[1][r] * ri * g1;
;         }
	v_pk_add_f32 v[0:1], v[0:1], v[20:21]
	s_nop 0
	v_pk_fma_f32 v[0:1], v[0:1], s[0:1], v[16:17] op_sel_hi:[1,0,0]
	s_nop 0
	v_mul_f32_e32 v20, 0x4b800000, v1
	v_cmp_gt_f32_e64 s[38:39], s90, v1
	v_cmp_gt_f32_e32 vcc, s90, v0
	s_nop 0
	v_cndmask_b32_e64 v1, v1, v20, s[38:39]
	v_rsq_f32_e32 v1, v1
	s_nop 0
	v_mul_f32_e32 v20, 0x45800000, v1
	v_cndmask_b32_e64 v1, v1, v20, s[38:39]
	v_mul_f32_e32 v2, v2, v1
	v_mul_f32_e32 v1, v3, v1
	v_mul_f32_e32 v2, v19, v2
	v_mul_f32_e32 v1, v18, v1
	ds_write2_b32 v152, v2, v1 offset0:128 offset1:160
	v_mul_f32_e32 v1, 0x4b800000, v0
	v_cndmask_b32_e32 v0, v0, v1, vcc
	v_rsq_f32_e32 v0, v0
	v_pk_mul_f32 v[2:3], v[144:145], v[144:145]
	v_mul_f32_e32 v1, 0x45800000, v0
	v_cndmask_b32_e32 v0, v0, v1, vcc
	v_mul_f32_e32 v1, v146, v0
	v_mul_f32_e32 v0, v147, v0
	v_mul_f32_e32 v1, v19, v1
	v_mul_f32_e32 v0, v18, v0
	ds_write2_b32 v152, v1, v0 offset0:192 offset1:224
	v_pk_mul_f32 v[0:1], v[4:5], v[4:5]
	v_mov_b32_e32 v20, v2
	v_mov_b32_e32 v21, v0
	v_mov_b32_e32 v0, v3
	v_pk_add_f32 v[0:1], v[20:21], v[0:1]
	v_add_u32_e32 v20, 0x800, v152
	s_waitcnt lgkmcnt(0)
	s_nop 1
	v_add_f32_dpp v0, v0, v0 quad_perm:[1,0,3,2] row_mask:0xf bank_mask:0xf
	v_add_f32_dpp v1, v1, v1 quad_perm:[1,0,3,2] row_mask:0xf bank_mask:0xf
	s_waitcnt lgkmcnt(0)
	s_nop 1
	v_add_f32_dpp v0, v0, v0 quad_perm:[2,3,0,1] row_mask:0xf bank_mask:0xf
	v_add_f32_dpp v1, v1, v1 quad_perm:[2,3,0,1] row_mask:0xf bank_mask:0xf
	s_waitcnt lgkmcnt(0)
	s_nop 1
	v_add_f32_dpp v0, v0, v0 row_half_mirror row_mask:0xf bank_mask:0xf
	v_add_f32_dpp v1, v1, v1 row_half_mirror row_mask:0xf bank_mask:0xf
	s_waitcnt lgkmcnt(0)
	s_nop 1
	v_add_f32_dpp v0, v0, v0 row_ror:8 row_mask:0xf bank_mask:0xf
	v_add_f32_dpp v1, v1, v1 row_ror:8 row_mask:0xf bank_mask:0xf
	ds_bpermute_b32 v3, v215, v1
	ds_bpermute_b32 v2, v215, v0
	s_waitcnt lgkmcnt(0)
	v_pk_add_f32 v[0:1], v[0:1], v[2:3]
	s_nop 0
	v_pk_fma_f32 v[0:1], v[0:1], s[0:1], v[16:17] op_sel_hi:[1,0,0]
	s_nop 0
	v_mul_f32_e32 v2, 0x4b800000, v1
	v_cmp_gt_f32_e64 s[38:39], s90, v1
	v_cmp_gt_f32_e32 vcc, s90, v0
	s_nop 0
	v_cndmask_b32_e64 v1, v1, v2, s[38:39]
	v_rsq_f32_e32 v1, v1
	s_nop 0
	v_mul_f32_e32 v2, 0x45800000, v1
	v_cndmask_b32_e64 v1, v1, v2, s[38:39]
	v_mul_f32_e32 v2, v4, v1
	v_mul_f32_e32 v1, v5, v1
	v_mul_f32_e32 v2, v19, v2
	v_mul_f32_e32 v1, v18, v1
	ds_write2_b32 v20, v2, v1 offset1:32
	v_mul_f32_e32 v1, 0x4b800000, v0
	v_cndmask_b32_e32 v0, v0, v1, vcc
	v_rsq_f32_e32 v0, v0
	v_pk_mul_f32 v[2:3], v[142:143], v[142:143]
	v_mul_f32_e32 v1, 0x45800000, v0
	v_cndmask_b32_e32 v0, v0, v1, vcc
	v_mul_f32_e32 v1, v144, v0
	v_mul_f32_e32 v0, v145, v0
	v_mul_f32_e32 v1, v19, v1
	v_mul_f32_e32 v0, v18, v0
	ds_write2_b32 v20, v1, v0 offset0:64 offset1:96
	v_pk_mul_f32 v[0:1], v[6:7], v[6:7]
	v_mov_b32_e32 v4, v2
	v_mov_b32_e32 v5, v0
	v_mov_b32_e32 v0, v3
	v_pk_add_f32 v[0:1], v[4:5], v[0:1]
	s_waitcnt lgkmcnt(0)
	s_nop 1
	v_add_f32_dpp v0, v0, v0 quad_perm:[1,0,3,2] row_mask:0xf bank_mask:0xf
	v_add_f32_dpp v1, v1, v1 quad_perm:[1,0,3,2] row_mask:0xf bank_mask:0xf
	s_waitcnt lgkmcnt(0)
	s_nop 1
	v_add_f32_dpp v0, v0, v0 quad_perm:[2,3,0,1] row_mask:0xf bank_mask:0xf
	v_add_f32_dpp v1, v1, v1 quad_perm:[2,3,0,1] row_mask:0xf bank_mask:0xf
	s_waitcnt lgkmcnt(0)
	s_nop 1
	v_add_f32_dpp v0, v0, v0 row_half_mirror row_mask:0xf bank_mask:0xf
	v_add_f32_dpp v1, v1, v1 row_half_mirror row_mask:0xf bank_mask:0xf
	s_waitcnt lgkmcnt(0)
	s_nop 1
	v_add_f32_dpp v0, v0, v0 row_ror:8 row_mask:0xf bank_mask:0xf
	v_add_f32_dpp v1, v1, v1 row_ror:8 row_mask:0xf bank_mask:0xf
	ds_bpermute_b32 v3, v215, v1
	ds_bpermute_b32 v2, v215, v0
	s_waitcnt lgkmcnt(0)
	v_pk_add_f32 v[0:1], v[0:1], v[2:3]
	s_nop 0
	v_pk_fma_f32 v[0:1], v[0:1], s[0:1], v[16:17] op_sel_hi:[1,0,0]
	s_nop 0
	v_mul_f32_e32 v2, 0x4b800000, v1
	v_cmp_gt_f32_e64 s[38:39], s90, v1
	v_cmp_gt_f32_e32 vcc, s90, v0
	s_nop 0
	v_cndmask_b32_e64 v1, v1, v2, s[38:39]
	v_rsq_f32_e32 v1, v1
	s_nop 0
	v_mul_f32_e32 v2, 0x45800000, v1
	v_cndmask_b32_e64 v1, v1, v2, s[38:39]
	v_mul_f32_e32 v2, v6, v1
	v_mul_f32_e32 v1, v7, v1
	v_mul_f32_e32 v2, v19, v2
	v_mul_f32_e32 v1, v18, v1
	ds_write2_b32 v20, v2, v1 offset0:128 offset1:160
	v_mul_f32_e32 v1, 0x4b800000, v0
	v_cndmask_b32_e32 v0, v0, v1, vcc
	v_rsq_f32_e32 v0, v0
	v_pk_mul_f32 v[2:3], v[140:141], v[140:141]
	v_add_u32_e32 v6, 0x1000, v152
	v_mov_b32_e32 v4, v2
	v_mul_f32_e32 v1, 0x45800000, v0
	v_cndmask_b32_e32 v0, v0, v1, vcc
	v_mul_f32_e32 v1, v142, v0
	v_mul_f32_e32 v0, v143, v0
	v_mul_f32_e32 v1, v19, v1
	v_mul_f32_e32 v0, v18, v0
	ds_write2_b32 v20, v1, v0 offset0:192 offset1:224
	v_pk_mul_f32 v[0:1], v[8:9], v[8:9]
	s_nop 0
	v_mov_b32_e32 v5, v0
	v_mov_b32_e32 v0, v3
	v_pk_add_f32 v[0:1], v[4:5], v[0:1]
	s_waitcnt lgkmcnt(0)
	s_nop 1
	v_add_f32_dpp v0, v0, v0 quad_perm:[1,0,3,2] row_mask:0xf bank_mask:0xf
	v_add_f32_dpp v1, v1, v1 quad_perm:[1,0,3,2] row_mask:0xf bank_mask:0xf
	s_waitcnt lgkmcnt(0)
	s_nop 1
	v_add_f32_dpp v0, v0, v0 quad_perm:[2,3,0,1] row_mask:0xf bank_mask:0xf
	v_add_f32_dpp v1, v1, v1 quad_perm:[2,3,0,1] row_mask:0xf bank_mask:0xf
	s_waitcnt lgkmcnt(0)
	s_nop 1
	v_add_f32_dpp v0, v0, v0 row_half_mirror row_mask:0xf bank_mask:0xf
	v_add_f32_dpp v1, v1, v1 row_half_mirror row_mask:0xf bank_mask:0xf
	s_waitcnt lgkmcnt(0)
	s_nop 1
	v_add_f32_dpp v0, v0, v0 row_ror:8 row_mask:0xf bank_mask:0xf
	v_add_f32_dpp v1, v1, v1 row_ror:8 row_mask:0xf bank_mask:0xf
	ds_bpermute_b32 v3, v215, v1
	ds_bpermute_b32 v2, v215, v0
	s_waitcnt lgkmcnt(0)
; #define LAS __attribute__((address_space(3)))
; DI int crow(int r, int hi) { return (r & 3) + 8 * (r >> 2) + 4 * hi; }
; DI void phase_ret_out(const Params& p, const Grp& G, int layer, LAS unsigned char* lds, int tid, int wave, int lane, bool dry) {
;     ...
; #pragma unroll
;         for (int r = 0; r < 16; ++r) {
;             float ss = o[0][r] * o[0][r] + o[1][r] * o[1][r]; ss = half_sum32(ss); const float ri = rsqrtf(ss * (1.0f / 64.0f) + EPSN);
;             LAS float* sp = stg + crow(r, hi) * 64 + l31; sp[0] = o[0][r] * ri * g0; sp[32] = o[1][r] * ri * g1;
;         }
	v_pk_add_f32 v[0:1], v[0:1], v[2:3]
	s_nop 0
	v_pk_fma_f32 v[0:1], v[0:1], s[0:1], v[16:17] op_sel_hi:[1,0,0]
	s_nop 0
	v_mul_f32_e32 v2, 0x4b800000, v1
	v_cmp_gt_f32_e64 s[38:39], s90, v1
	v_cmp_gt_f32_e32 vcc, s90, v0
	s_nop 0
	v_cndmask_b32_e64 v1, v1, v2, s[38:39]
	v_rsq_f32_e32 v1, v1
	s_nop 0
	v_mul_f32_e32 v2, 0x45800000, v1
	v_cndmask_b32_e64 v1, v1, v2, s[38:39]
	v_mul_f32_e32 v2, v8, v1
	v_mul_f32_e32 v1, v9, v1
	v_mul_f32_e32 v2, v19, v2
	v_mul_f32_e32 v1, v18, v1
	ds_write2_b32 v6, v2, v1 offset1:32
	v_mul_f32_e32 v1, 0x4b800000, v0
	v_cndmask_b32_e32 v0, v0, v1, vcc
	v_rsq_f32_e32 v0, v0
	v_pk_mul_f32 v[2:3], v[138:139], v[138:139]
	v_mul_f32_e32 v1, 0x45800000, v0
	v_cndmask_b32_e32 v0, v0, v1, vcc
	v_mul_f32_e32 v1, v140, v0
	v_mul_f32_e32 v0, v141, v0
	v_mul_f32_e32 v1, v19, v1
	v_mul_f32_e32 v0, v18, v0
	ds_write2_b32 v6, v1, v0 offset0:64 offset1:96
	v_pk_mul_f32 v[0:1], v[10:11], v[10:11]
	v_mov_b32_e32 v4, v2
	v_mov_b32_e32 v5, v0
	v_mov_b32_e32 v0, v3
	v_pk_add_f32 v[0:1], v[4:5], v[0:1]
	s_waitcnt lgkmcnt(0)
	s_nop 1
	v_add_f32_dpp v0, v0, v0 quad_perm:[1,0,3,2] row_mask:0xf bank_mask:0xf
	v_add_f32_dpp v1, v1, v1 quad_perm:[1,0,3,2] row_mask:0xf bank_mask:0xf
	s_waitcnt lgkmcnt(0)
	s_nop 1
	v_add_f32_dpp v0, v0, v0 quad_perm:[2,3,0,1] row_mask:0xf bank_mask:0xf
	v_add_f32_dpp v1, v1, v1 quad_perm:[2,3,0,1] row_mask:0xf bank_mask:0xf
	s_waitcnt lgkmcnt(0)
	s_nop 1
	v_add_f32_dpp v0, v0, v0 row_half_mirror row_mask:0xf bank_mask:0xf
	v_add_f32_dpp v1, v1, v1 row_half_mirror row_mask:0xf bank_mask:0xf
	s_waitcnt lgkmcnt(0)
	s_nop 1
	v_add_f32_dpp v0, v0, v0 row_ror:8 row_mask:0xf bank_mask:0xf
	v_add_f32_dpp v1, v1, v1 row_ror:8 row_mask:0xf bank_mask:0xf
	ds_bpermute_b32 v3, v215, v1
	ds_bpermute_b32 v2, v215, v0
	s_waitcnt lgkmcnt(0)
	v_pk_add_f32 v[0:1], v[0:1], v[2:3]
	s_nop 0
	v_pk_fma_f32 v[0:1], v[0:1], s[0:1], v[16:17] op_sel_hi:[1,0,0]
	s_nop 0
	v_mul_f32_e32 v2, 0x4b800000, v1
	v_cmp_gt_f32_e64 s[38:39], s90, v1
	v_cmp_gt_f32_e32 vcc, s90, v0
	s_nop 0
	v_cndmask_b32_e64 v1, v1, v2, s[38:39]
	v_rsq_f32_e32 v1, v1
	s_nop 0
	v_mul_f32_e32 v2, 0x45800000, v1
	v_cndmask_b32_e64 v1, v1, v2, s[38:39]
	v_mul_f32_e32 v2, v10, v1
	v_mul_f32_e32 v1, v11, v1
	v_mul_f32_e32 v2, v19, v2
	v_mul_f32_e32 v1, v18, v1
	ds_write2_b32 v6, v2, v1 offset0:128 offset1:160
	v_mul_f32_e32 v1, 0x4b800000, v0
	v_cndmask_b32_e32 v0, v0, v1, vcc
	v_rsq_f32_e32 v0, v0
	v_pk_mul_f32 v[2:3], v[136:137], v[136:137]
	v_mul_f32_e32 v1, 0x45800000, v0
	v_cndmask_b32_e32 v0, v0, v1, vcc
	v_mul_f32_e32 v1, v138, v0
	v_mul_f32_e32 v0, v139, v0
	v_mul_f32_e32 v1, v19, v1
	v_mul_f32_e32 v0, v18, v0
	ds_write2_b32 v6, v1, v0 offset0:192 offset1:224
	v_pk_mul_f32 v[0:1], v[12:13], v[12:13]
	v_mov_b32_e32 v4, v2
	v_mov_b32_e32 v5, v0
	v_mov_b32_e32 v0, v3
	v_pk_add_f32 v[0:1], v[4:5], v[0:1]
	v_add_u32_e32 v6, 0x1800, v152
	s_waitcnt lgkmcnt(0)
	s_nop 1
	v_add_f32_dpp v0, v0, v0 quad_perm:[1,0,3,2] row_mask:0xf bank_mask:0xf
	v_add_f32_dpp v1, v1, v1 quad_perm:[1,0,3,2] row_mask:0xf bank_mask:0xf
	s_waitcnt lgkmcnt(0)
	s_nop 1
	v_add_f32_dpp v0, v0, v0 quad_perm:[2,3,0,1] row_mask:0xf bank_mask:0xf
	v_add_f32_dpp v1, v1, v1 quad_perm:[2,3,0,1] row_mask:0xf bank_mask:0xf
	s_waitcnt lgkmcnt(0)
	s_nop 1
	v_add_f32_dpp v0, v0, v0 row_half_mirror row_mask:0xf bank_mask:0xf
	v_add_f32_dpp v1, v1, v1 row_half_mirror row_mask:0xf bank_mask:0xf
	s_waitcnt lgkmcnt(0)
	s_nop 1
	v_add_f32_dpp v0, v0, v0 row_ror:8 row_mask:0xf bank_mask:0xf
	v_add_f32_dpp v1, v1, v1 row_ror:8 row_mask:0xf bank_mask:0xf
	ds_bpermute_b32 v3, v215, v1
	ds_bpermute_b32 v2, v215, v0
	s_waitcnt lgkmcnt(0)
	v_pk_add_f32 v[0:1], v[0:1], v[2:3]
	s_nop 0
	v_pk_fma_f32 v[0:1], v[0:1], s[0:1], v[16:17] op_sel_hi:[1,0,0]
	s_nop 0
	v_mul_f32_e32 v2, 0x4b800000, v1
	v_cmp_gt_f32_e64 s[38:39], s90, v1
	v_cmp_gt_f32_e32 vcc, s90, v0
	s_nop 0
	v_cndmask_b32_e64 v1, v1, v2, s[38:39]
	v_rsq_f32_e32 v1, v1
	s_nop 0
	v_mul_f32_e32 v2, 0x45800000, v1
	v_cndmask_b32_e64 v1, v1, v2, s[38:39]
	v_mul_f32_e32 v2, v12, v1
	v_mul_f32_e32 v1, v13, v1
	v_mul_f32_e32 v2, v19, v2
	v_mul_f32_e32 v1, v18, v1
	ds_write2_b32 v6, v2, v1 offset1:32
	v_mul_f32_e32 v1, 0x4b800000, v0
	v_cndmask_b32_e32 v0, v0, v1, vcc
	v_rsq_f32_e32 v0, v0
	v_pk_mul_f32 v[2:3], v[134:135], v[134:135]
	v_mul_f32_e32 v1, 0x45800000, v0
	v_cndmask_b32_e32 v0, v0, v1, vcc
	v_mul_f32_e32 v1, v136, v0
	v_mul_f32_e32 v0, v137, v0
	v_mul_f32_e32 v1, v19, v1
	v_mul_f32_e32 v0, v18, v0
	ds_write2_b32 v6, v1, v0 offset0:64 offset1:96
	v_pk_mul_f32 v[0:1], v[14:15], v[14:15]
	v_mov_b32_e32 v4, v2
	v_mov_b32_e32 v5, v0
	v_mov_b32_e32 v0, v3
	v_pk_add_f32 v[0:1], v[4:5], v[0:1]
	s_waitcnt lgkmcnt(0)
	s_nop 1
	v_add_f32_dpp v0, v0, v0 quad_perm:[1,0,3,2] row_mask:0xf bank_mask:0xf
	v_add_f32_dpp v1, v1, v1 quad_perm:[1,0,3,2] row_mask:0xf bank_mask:0xf
	s_waitcnt lgkmcnt(0)
	s_nop 1
	v_add_f32_dpp v0, v0, v0 quad_perm:[2,3,0,1] row_mask:0xf bank_mask:0xf
	v_add_f32_dpp v1, v1, v1 quad_perm:[2,3,0,1] row_mask:0xf bank_mask:0xf
	s_waitcnt lgkmcnt(0)
	s_nop 1
	v_add_f32_dpp v0, v0, v0 row_half_mirror row_mask:0xf bank_mask:0xf
	v_add_f32_dpp v1, v1, v1 row_half_mirror row_mask:0xf bank_mask:0xf
	s_waitcnt lgkmcnt(0)
	s_nop 1
	v_add_f32_dpp v0, v0, v0 row_ror:8 row_mask:0xf bank_mask:0xf
	v_add_f32_dpp v1, v1, v1 row_ror:8 row_mask:0xf bank_mask:0xf
	ds_bpermute_b32 v3, v215, v1
	ds_bpermute_b32 v2, v215, v0
	s_waitcnt lgkmcnt(0)
; #define LAS __attribute__((address_space(3)))
; DI unsigned pk2(float lo, float hi) { typedef float f2 __attribute__((ext_vector_type(2))); typedef __bf16 b2 __attribute__((ext_vector_type(2))); f2 v = {lo, hi}; b2 b = __builtin_convertvector(v, b2); return __builtin_bit_cast(unsigned, b); }
; DI float bf_lo(unsigned w) { return __uint_as_float(w << 16); }
; DI float bf_hi(unsigned w) { return __uint_as_float(w & 0xffff0000u); }
; DI int crow(int r, int hi) { return (r & 3) + 8 * (r >> 2) + 4 * hi; }
; DI void phase_ret_out(const Params& p, const Grp& G, int layer, LAS unsigned char* lds, int tid, int wave, int lane, bool dry) {
;     ...
;             float ss = o[0][r] * o[0][r] + o[1][r] * o[1][r]; ss = half_sum32(ss); const float ri = rsqrtf(ss * (1.0f / 64.0f) + EPSN);
;             LAS float* sp = stg + crow(r, hi) * 64 + l31; sp[0] = o[0][r] * ri * g0; sp[32] = o[1][r] * ri * g1;
;         }
;         asm volatile("s_waitcnt lgkmcnt(0)" ::: "memory");
;         { int lv = lane; asm volatile("" : "+v"(lv));
;           bf16_t* ob = (dry ? (bf16_t*)(p.ws + OFF_DUMMY) : mix + row0 * MIXW) + (size_t)(32 * qg) * MIXW + 512 + head * 64; const bf16_t* gb = rest + (row0 + 32 * qg) * RESTW + R_RG + head * 64;
; #pragma unroll
;           for (int i = 0; i < 4; ++i) { const int q = lv + 64 * i, row = q >> 3, ch = q & 7;
;             const f32x4 a0 = *(const LAS f32x4*)(stg + row * 64 + ch * 8), a1 = *(const LAS f32x4*)(stg + row * 64 + ch * 8 + 4);
;             const u32x4 gw = gwv[i];
;             float gv[8] = {bf_lo(gw.x), bf_hi(gw.x), bf_lo(gw.y), bf_hi(gw.y), bf_lo(gw.z), bf_hi(gw.z), bf_lo(gw.w), bf_hi(gw.w)}; float ov[8];
; #pragma unroll
;             for (int e = 0; e < 8; ++e) ov[e] = (e < 4 ? a0[e & 3] : a1[e & 3]) * (gv[e] * __builtin_amdgcn_rcpf(1.f + __expf(-gv[e])));
;             u32x4 w; w.x = pk2(ov[0], ov[1]); w.y = pk2(ov[2], ov[3]); w.z = pk2(ov[4], ov[5]); w.w = pk2(ov[6], ov[7]);
;             *(u32x4*)(ob + (size_t)row * MIXW + ch * 8) = w; } }
	v_pk_add_f32 v[0:1], v[0:1], v[2:3]
	s_nop 0
	v_pk_fma_f32 v[0:1], v[0:1], s[0:1], v[16:17] op_sel_hi:[1,0,0]
	s_lshl_b64 s[0:1], s[42:43], 11
	v_mul_f32_e32 v2, 0x4b800000, v1
	v_cmp_gt_f32_e64 s[38:39], s90, v1
	v_cmp_gt_f32_e32 vcc, s90, v0
	s_add_u32 s0, s45, s0
	v_cndmask_b32_e64 v1, v1, v2, s[38:39]
	v_rsq_f32_e32 v1, v1
	s_addc_u32 s1, s52, s1
	s_lshl_b32 s4, s4, 1
	s_add_u32 s0, s0, s4
	v_mul_f32_e32 v2, 0x45800000, v1
	v_cndmask_b32_e64 v1, v1, v2, s[38:39]
	v_mul_f32_e32 v2, v14, v1
	v_mul_f32_e32 v1, v15, v1
	v_mul_f32_e32 v2, v19, v2
	v_mul_f32_e32 v1, v18, v1
	ds_write2_b32 v6, v2, v1 offset0:128 offset1:160
	v_mul_f32_e32 v1, 0x4b800000, v0
	v_cndmask_b32_e32 v0, v0, v1, vcc
	v_lshlrev_b32_e32 v14, 16, v108
	v_rsq_f32_e32 v0, v0
	v_mul_f32_e32 v13, 0xbfb8aa3b, v14
	v_exp_f32_e32 v13, v13
	v_and_b32_e32 v15, 0xffff0000, v108
	v_mul_f32_e32 v1, 0x45800000, v0
	v_cndmask_b32_e32 v0, v0, v1, vcc
	v_add_f32_e32 v13, 1.0, v13
	v_mul_f32_e32 v1, v134, v0
	v_mul_f32_e32 v0, v135, v0
	v_rcp_f32_e32 v16, v13
	v_mul_f32_e32 v13, 0xbfb8aa3b, v15
	v_mul_f32_e32 v1, v19, v1
	v_mul_f32_e32 v0, v18, v0
	v_exp_f32_e32 v13, v13
	ds_write2_b32 v6, v1, v0 offset0:192 offset1:224
	v_mov_b32_e32 v2, v129
	s_waitcnt lgkmcnt(0)
	v_add_f32_e32 v13, 1.0, v13
	v_lshlrev_b32_e32 v0, 3, v2
	v_and_b32_e32 v0, 56, v0
	v_lshl_add_u32 v3, v0, 2, s60
	v_ashrrev_i32_e32 v12, 3, v2
	v_lshl_add_u32 v8, v12, 8, v3
	v_rcp_f32_e32 v17, v13
	ds_read_b128 v[4:7], v8
	ds_read_b128 v[8:11], v8 offset:16
	s_addc_u32 s1, s1, 0
	v_lshlrev_b32_e32 v192, 1, v0
	v_pk_mul_f32 v[14:15], v[16:17], v[14:15]
	v_lshl_add_u64 v[0:1], s[0:1], 0, v[192:193]
	s_waitcnt lgkmcnt(1)
	v_pk_mul_f32 v[4:5], v[14:15], v[4:5]
	v_lshlrev_b32_e32 v14, 16, v109
	v_mul_f32_e32 v13, 0xbfb8aa3b, v14
	v_exp_f32_e32 v13, v13
	v_and_b32_e32 v15, 0xffff0000, v109
	v_cvt_pk_bf16_f32 v4, v4, v5
	s_and_b64 vcc, exec, s[40:41]
	v_add_f32_e32 v13, 1.0, v13
	v_rcp_f32_e32 v16, v13
	v_mul_f32_e32 v13, 0xbfb8aa3b, v15
	v_exp_f32_e32 v13, v13
	s_nop 0
	v_add_f32_e32 v13, 1.0, v13
	v_rcp_f32_e32 v17, v13
	s_nop 0
	v_pk_mul_f32 v[14:15], v[16:17], v[14:15]
	s_nop 0
	v_pk_mul_f32 v[6:7], v[14:15], v[6:7]
	v_lshlrev_b32_e32 v14, 16, v110
	v_mul_f32_e32 v13, 0xbfb8aa3b, v14
	v_exp_f32_e32 v13, v13
	v_and_b32_e32 v15, 0xffff0000, v110
	v_cvt_pk_bf16_f32 v5, v6, v7
	v_add_f32_e32 v13, 1.0, v13
	v_rcp_f32_e32 v16, v13
	v_mul_f32_e32 v13, 0xbfb8aa3b, v15
	v_exp_f32_e32 v13, v13
	s_nop 0
	v_add_f32_e32 v13, 1.0, v13
	v_rcp_f32_e32 v17, v13
	s_nop 0
	v_pk_mul_f32 v[14:15], v[16:17], v[14:15]
	s_waitcnt lgkmcnt(0)
	v_pk_mul_f32 v[8:9], v[14:15], v[8:9]
	v_lshlrev_b32_e32 v14, 16, v111
	v_mul_f32_e32 v13, 0xbfb8aa3b, v14
	v_exp_f32_e32 v13, v13
	v_and_b32_e32 v15, 0xffff0000, v111
	v_cvt_pk_bf16_f32 v6, v8, v9
	v_add_f32_e32 v13, 1.0, v13
	v_rcp_f32_e32 v16, v13
	v_mul_f32_e32 v13, 0xbfb8aa3b, v15
	v_exp_f32_e32 v13, v13
	s_nop 0
	v_add_f32_e32 v13, 1.0, v13
	v_rcp_f32_e32 v17, v13
	v_ashrrev_i32_e32 v13, 31, v12
	v_lshlrev_b64 v[8:9], 11, v[12:13]
	v_lshl_add_u64 v[8:9], v[0:1], 0, v[8:9]
	v_pk_mul_f32 v[14:15], v[16:17], v[14:15]
	s_nop 0
	v_pk_mul_f32 v[10:11], v[14:15], v[10:11]
	v_lshlrev_b32_e32 v14, 16, v104
	v_mul_f32_e32 v13, 0xbfb8aa3b, v14
	v_exp_f32_e32 v13, v13
	v_and_b32_e32 v15, 0xffff0000, v104
	v_cvt_pk_bf16_f32 v7, v10, v11
	global_store_dwordx4 v[8:9], v[4:7], off offset:1024
	v_add_f32_e32 v13, 1.0, v13
	v_rcp_f32_e32 v16, v13
	v_mul_f32_e32 v13, 0xbfb8aa3b, v15
	v_exp_f32_e32 v13, v13
	v_add_u32_e32 v4, 64, v2
	v_ashrrev_i32_e32 v12, 3, v4
	v_lshl_add_u32 v8, v12, 8, v3
	v_add_f32_e32 v13, 1.0, v13
	v_rcp_f32_e32 v17, v13
	ds_read_b128 v[4:7], v8
	ds_read_b128 v[8:11], v8 offset:16
	v_pk_mul_f32 v[14:15], v[16:17], v[14:15]
	s_waitcnt lgkmcnt(1)
	v_pk_mul_f32 v[4:5], v[14:15], v[4:5]
	v_lshlrev_b32_e32 v14, 16, v105
	v_mul_f32_e32 v13, 0xbfb8aa3b, v14
	v_exp_f32_e32 v13, v13
	v_and_b32_e32 v15, 0xffff0000, v105
	v_cvt_pk_bf16_f32 v4, v4, v5
	v_add_f32_e32 v13, 1.0, v13
	v_rcp_f32_e32 v16, v13
	v_mul_f32_e32 v13, 0xbfb8aa3b, v15
	v_exp_f32_e32 v13, v13
	s_nop 0
	v_add_f32_e32 v13, 1.0, v13
	v_rcp_f32_e32 v17, v13
	s_nop 0
	v_pk_mul_f32 v[14:15], v[16:17], v[14:15]
	s_nop 0
	v_pk_mul_f32 v[6:7], v[14:15], v[6:7]
	v_lshlrev_b32_e32 v14, 16, v106
	v_mul_f32_e32 v13, 0xbfb8aa3b, v14
	v_exp_f32_e32 v13, v13
	v_and_b32_e32 v15, 0xffff0000, v106
	v_cvt_pk_bf16_f32 v5, v6, v7
	v_add_f32_e32 v13, 1.0, v13
	v_rcp_f32_e32 v16, v13
	v_mul_f32_e32 v13, 0xbfb8aa3b, v15
	v_exp_f32_e32 v13, v13
	s_nop 0
	v_add_f32_e32 v13, 1.0, v13
	v_rcp_f32_e32 v17, v13
	s_nop 0
	v_pk_mul_f32 v[14:15], v[16:17], v[14:15]
	s_waitcnt lgkmcnt(0)
; #define LAS __attribute__((address_space(3)))
; DI unsigned pk2(float lo, float hi) { typedef float f2 __attribute__((ext_vector_type(2))); typedef __bf16 b2 __attribute__((ext_vector_type(2))); f2 v = {lo, hi}; b2 b = __builtin_convertvector(v, b2); return __builtin_bit_cast(unsigned, b); }
; DI float bf_lo(unsigned w) { return __uint_as_float(w << 16); }
; DI float bf_hi(unsigned w) { return __uint_as_float(w & 0xffff0000u); }
; DI void phase_ret_out(const Params& p, const Grp& G, int layer, LAS unsigned char* lds, int tid, int wave, int lane, bool dry) {
;     ...
;         { int lv = lane; asm volatile("" : "+v"(lv));
;           bf16_t* ob = (dry ? (bf16_t*)(p.ws + OFF_DUMMY) : mix + row0 * MIXW) + (size_t)(32 * qg) * MIXW + 512 + head * 64; const bf16_t* gb = rest + (row0 + 32 * qg) * RESTW + R_RG + head * 64;
; #pragma unroll
;           for (int i = 0; i < 4; ++i) { const int q = lv + 64 * i, row = q >> 3, ch = q & 7;
;             const f32x4 a0 = *(const LAS f32x4*)(stg + row * 64 + ch * 8), a1 = *(const LAS f32x4*)(stg + row * 64 + ch * 8 + 4);
;             const u32x4 gw = gwv[i];
;             float gv[8] = {bf_lo(gw.x), bf_hi(gw.x), bf_lo(gw.y), bf_hi(gw.y), bf_lo(gw.z), bf_hi(gw.z), bf_lo(gw.w), bf_hi(gw.w)}; float ov[8];
; #pragma unroll
;             for (int e = 0; e < 8; ++e) ov[e] = (e < 4 ? a0[e & 3] : a1[e & 3]) * (gv[e] * __builtin_amdgcn_rcpf(1.f + __expf(-gv[e])));
;             u32x4 w; w.x = pk2(ov[0], ov[1]); w.y = pk2(ov[2], ov[3]); w.z = pk2(ov[4], ov[5]); w.w = pk2(ov[6], ov[7]);
;             *(u32x4*)(ob + (size_t)row * MIXW + ch * 8) = w; } }
	v_pk_mul_f32 v[8:9], v[14:15], v[8:9]
	v_lshlrev_b32_e32 v14, 16, v107
	v_mul_f32_e32 v13, 0xbfb8aa3b, v14
	v_exp_f32_e32 v13, v13
	v_and_b32_e32 v15, 0xffff0000, v107
	v_cvt_pk_bf16_f32 v6, v8, v9
	v_add_f32_e32 v13, 1.0, v13
	v_rcp_f32_e32 v16, v13
	v_mul_f32_e32 v13, 0xbfb8aa3b, v15
	v_exp_f32_e32 v13, v13
	s_nop 0
	v_add_f32_e32 v13, 1.0, v13
	v_rcp_f32_e32 v17, v13
	v_ashrrev_i32_e32 v13, 31, v12
	v_lshlrev_b64 v[8:9], 11, v[12:13]
	v_lshl_add_u64 v[8:9], v[0:1], 0, v[8:9]
	v_pk_mul_f32 v[14:15], v[16:17], v[14:15]
	s_nop 0
	v_pk_mul_f32 v[10:11], v[14:15], v[10:11]
	v_lshlrev_b32_e32 v14, 16, v100
	v_mul_f32_e32 v13, 0xbfb8aa3b, v14
	v_exp_f32_e32 v13, v13
	v_and_b32_e32 v15, 0xffff0000, v100
	v_cvt_pk_bf16_f32 v7, v10, v11
	global_store_dwordx4 v[8:9], v[4:7], off offset:1024
	v_add_f32_e32 v13, 1.0, v13
	v_rcp_f32_e32 v16, v13
	v_mul_f32_e32 v13, 0xbfb8aa3b, v15
	v_exp_f32_e32 v13, v13
	v_add_u32_e32 v4, 0x80, v2
	v_ashrrev_i32_e32 v12, 3, v4
	v_lshl_add_u32 v8, v12, 8, v3
	v_add_f32_e32 v13, 1.0, v13
	v_rcp_f32_e32 v17, v13
	ds_read_b128 v[4:7], v8
	ds_read_b128 v[8:11], v8 offset:16
	v_add_u32_e32 v2, 0xc0, v2
	v_pk_mul_f32 v[14:15], v[16:17], v[14:15]
	s_waitcnt lgkmcnt(1)
	v_pk_mul_f32 v[4:5], v[14:15], v[4:5]
	v_lshlrev_b32_e32 v14, 16, v101
	v_mul_f32_e32 v13, 0xbfb8aa3b, v14
	v_exp_f32_e32 v13, v13
	v_and_b32_e32 v15, 0xffff0000, v101
	v_cvt_pk_bf16_f32 v4, v4, v5
	v_add_f32_e32 v13, 1.0, v13
	v_rcp_f32_e32 v16, v13
	v_mul_f32_e32 v13, 0xbfb8aa3b, v15
	v_exp_f32_e32 v13, v13
	s_nop 0
	v_add_f32_e32 v13, 1.0, v13
	v_rcp_f32_e32 v17, v13
	s_nop 0
	v_pk_mul_f32 v[14:15], v[16:17], v[14:15]
	s_nop 0
	v_pk_mul_f32 v[6:7], v[14:15], v[6:7]
	v_lshlrev_b32_e32 v14, 16, v102
	v_mul_f32_e32 v13, 0xbfb8aa3b, v14
	v_exp_f32_e32 v13, v13
	v_and_b32_e32 v15, 0xffff0000, v102
	v_cvt_pk_bf16_f32 v5, v6, v7
	v_add_f32_e32 v13, 1.0, v13
	v_rcp_f32_e32 v16, v13
	v_mul_f32_e32 v13, 0xbfb8aa3b, v15
	v_exp_f32_e32 v13, v13
	s_nop 0
	v_add_f32_e32 v13, 1.0, v13
	v_rcp_f32_e32 v17, v13
	s_nop 0
	v_pk_mul_f32 v[14:15], v[16:17], v[14:15]
	s_waitcnt lgkmcnt(0)
	v_pk_mul_f32 v[8:9], v[14:15], v[8:9]
	v_lshlrev_b32_e32 v14, 16, v103
	v_mul_f32_e32 v13, 0xbfb8aa3b, v14
	v_exp_f32_e32 v13, v13
	v_and_b32_e32 v15, 0xffff0000, v103
	v_cvt_pk_bf16_f32 v6, v8, v9
	v_add_f32_e32 v13, 1.0, v13
	v_rcp_f32_e32 v16, v13
	v_mul_f32_e32 v13, 0xbfb8aa3b, v15
	v_exp_f32_e32 v13, v13
	s_nop 0
	v_add_f32_e32 v13, 1.0, v13
	v_rcp_f32_e32 v17, v13
	v_ashrrev_i32_e32 v13, 31, v12
	v_lshlrev_b64 v[8:9], 11, v[12:13]
	v_lshlrev_b32_e32 v12, 16, v96
	v_pk_mul_f32 v[14:15], v[16:17], v[14:15]
	v_and_b32_e32 v13, 0xffff0000, v96
	v_pk_mul_f32 v[10:11], v[14:15], v[10:11]
	v_lshl_add_u64 v[8:9], v[0:1], 0, v[8:9]
	v_cvt_pk_bf16_f32 v7, v10, v11
	v_mul_f32_e32 v11, 0xbfb8aa3b, v12
	v_exp_f32_e32 v11, v11
	v_ashrrev_i32_e32 v10, 3, v2
	global_store_dwordx4 v[8:9], v[4:7], off offset:1024
	v_add_f32_e32 v11, 1.0, v11
	v_rcp_f32_e32 v14, v11
	v_mul_f32_e32 v11, 0xbfb8aa3b, v13
	v_exp_f32_e32 v11, v11
	v_lshl_add_u32 v6, v10, 8, v3
	ds_read_b128 v[2:5], v6
	ds_read_b128 v[6:9], v6 offset:16
	v_add_f32_e32 v11, 1.0, v11
	v_rcp_f32_e32 v15, v11
	s_nop 0
	v_pk_mul_f32 v[12:13], v[14:15], v[12:13]
	s_waitcnt lgkmcnt(1)
	v_pk_mul_f32 v[2:3], v[12:13], v[2:3]
	v_lshlrev_b32_e32 v12, 16, v97
	v_mul_f32_e32 v11, 0xbfb8aa3b, v12
	v_exp_f32_e32 v11, v11
	v_and_b32_e32 v13, 0xffff0000, v97
	v_cvt_pk_bf16_f32 v2, v2, v3
	v_add_f32_e32 v11, 1.0, v11
	v_rcp_f32_e32 v14, v11
	v_mul_f32_e32 v11, 0xbfb8aa3b, v13
	v_exp_f32_e32 v11, v11
	s_nop 0
	v_add_f32_e32 v11, 1.0, v11
	v_rcp_f32_e32 v15, v11
	s_nop 0
	v_pk_mul_f32 v[12:13], v[14:15], v[12:13]
	s_nop 0
	v_pk_mul_f32 v[4:5], v[12:13], v[4:5]
	v_lshlrev_b32_e32 v12, 16, v98
	v_mul_f32_e32 v11, 0xbfb8aa3b, v12
	v_exp_f32_e32 v11, v11
	v_and_b32_e32 v13, 0xffff0000, v98
	v_cvt_pk_bf16_f32 v3, v4, v5
	v_add_f32_e32 v11, 1.0, v11
	v_rcp_f32_e32 v14, v11
	v_mul_f32_e32 v11, 0xbfb8aa3b, v13
	v_exp_f32_e32 v11, v11
	s_nop 0
	v_add_f32_e32 v11, 1.0, v11
	v_rcp_f32_e32 v15, v11
	s_nop 0
	v_pk_mul_f32 v[12:13], v[14:15], v[12:13]
	s_waitcnt lgkmcnt(0)
	v_pk_mul_f32 v[6:7], v[12:13], v[6:7]
	v_lshlrev_b32_e32 v12, 16, v99
	v_mul_f32_e32 v11, 0xbfb8aa3b, v12
	v_exp_f32_e32 v11, v11
	v_and_b32_e32 v13, 0xffff0000, v99
	v_cvt_pk_bf16_f32 v4, v6, v7
	v_add_f32_e32 v11, 1.0, v11
	v_rcp_f32_e32 v14, v11
	v_mul_f32_e32 v11, 0xbfb8aa3b, v13
	v_exp_f32_e32 v11, v11
	s_nop 0
	v_add_f32_e32 v11, 1.0, v11
	v_rcp_f32_e32 v15, v11
	v_ashrrev_i32_e32 v11, 31, v10
	v_lshlrev_b64 v[6:7], 11, v[10:11]
	v_lshl_add_u64 v[0:1], v[0:1], 0, v[6:7]
	v_pk_mul_f32 v[12:13], v[14:15], v[12:13]
	s_nop 0
	v_pk_mul_f32 v[8:9], v[12:13], v[8:9]
	s_nop 0
	v_cvt_pk_bf16_f32 v5, v8, v9
	global_store_dwordx4 v[0:1], v[2:5], off offset:1024
	s_cbranch_vccz .LBB0_419
